# K-loops: phase-1 scalar pointer/cselect ops moved to the tail of phase 8 MFMA burst (+ pre-loop copy), on top of read rebalancing
# baseline (speedup 1.0000x reference)
.LBB0_266:
	s_xor_b64 s[2:3], s[2:3], -1
	s_mov_b32 s34, s74
	s_add_i32 s74, s74, 1
	s_cmp_lt_u32 s34, 5
	s_mov_b64 s[4:5], s[10:11]
	s_mov_b32 s10, s75
	s_cselect_b64 s[14:15], -1, 0
	s_add_i32 s75, s74, s16
	s_mov_b64 s[12:13], s[8:9]
	s_and_b64 s[8:9], s[14:15], exec
	s_cselect_b32 s8, s75, s10
	s_cselect_b32 s10, s6, s6
	s_ashr_i32 s11, s10, 31
	s_lshl_b64 s[10:11], s[10:11], 19
	s_add_u32 s10, s80, s10
	s_addc_u32 s11, s81, s11
	s_and_b64 s[44:45], s[14:15], exec
	s_cselect_b32 s44, s11, s5
	s_cselect_b32 s45, s10, s4
	s_ashr_i32 s9, s8, 31
	s_lshl_b64 s[8:9], s[8:9], 19
	v_readlane_b32 s47, v255, 14
	s_add_u32 s8, s47, s8
	v_readlane_b32 s47, v255, 15
	s_addc_u32 s9, s47, s9
	s_and_b64 s[14:15], s[14:15], exec
	s_cselect_b32 s47, s9, s13
	s_cselect_b32 s55, s8, s12
	s_add_u32 s4, s4, 0x40080
	s_addc_u32 s5, s5, 0
	s_add_u32 s78, s12, 0x100
	v_mov_b32_e32 v2, 0
	s_addc_u32 s79, s13, 0
	s_mov_b32 s85, -2
	v_mov_b32_e32 v3, v2
	s_waitcnt lgkmcnt(0)
	v_mov_b32_e32 v4, v2
	v_mov_b32_e32 v5, v2
	v_mov_b32_e32 v6, v2
	v_mov_b32_e32 v7, v2
	v_mov_b32_e32 v8, v2
	v_mov_b32_e32 v9, v2
	v_mov_b32_e32 v18, v2
	v_mov_b32_e32 v19, v2
	v_mov_b32_e32 v20, v2
	v_mov_b32_e32 v21, v2
	v_mov_b32_e32 v22, v2
	v_mov_b32_e32 v23, v2
	v_mov_b32_e32 v24, v2
	v_mov_b32_e32 v25, v2
	v_mov_b32_e32 v34, v2
	v_mov_b32_e32 v35, v2
	v_mov_b32_e32 v36, v2
	v_mov_b32_e32 v37, v2
	v_mov_b32_e32 v38, v2
	v_mov_b32_e32 v39, v2
	v_mov_b32_e32 v40, v2
	v_mov_b32_e32 v41, v2
	v_mov_b32_e32 v50, v2
	v_mov_b32_e32 v51, v2
	v_mov_b32_e32 v52, v2
	v_mov_b32_e32 v53, v2
	v_mov_b32_e32 v54, v2
	v_mov_b32_e32 v55, v2
	v_mov_b32_e32 v56, v2
	v_mov_b32_e32 v57, v2
	v_mov_b32_e32 v10, v2
	v_mov_b32_e32 v11, v2
	v_mov_b32_e32 v12, v2
	v_mov_b32_e32 v13, v2
	v_mov_b32_e32 v14, v2
	v_mov_b32_e32 v15, v2
	v_mov_b32_e32 v16, v2
	v_mov_b32_e32 v17, v2
	v_mov_b32_e32 v26, v2
	v_mov_b32_e32 v27, v2
	v_mov_b32_e32 v28, v2
	v_mov_b32_e32 v29, v2
	v_mov_b32_e32 v30, v2
	v_mov_b32_e32 v31, v2
	v_mov_b32_e32 v32, v2
	v_mov_b32_e32 v33, v2
	v_mov_b32_e32 v42, v2
	v_mov_b32_e32 v43, v2
	v_mov_b32_e32 v44, v2
	v_mov_b32_e32 v45, v2
	v_mov_b32_e32 v46, v2
	v_mov_b32_e32 v47, v2
	v_mov_b32_e32 v48, v2
	v_mov_b32_e32 v49, v2
	v_mov_b32_e32 v58, v2
	v_mov_b32_e32 v59, v2
	v_mov_b32_e32 v60, v2
	v_mov_b32_e32 v61, v2
	v_mov_b32_e32 v62, v2
	v_mov_b32_e32 v63, v2
	v_mov_b32_e32 v64, v2
	v_mov_b32_e32 v65, v2
	v_mov_b32_e32 v66, v2
	v_mov_b32_e32 v67, v2
	v_mov_b32_e32 v68, v2
	v_mov_b32_e32 v69, v2
	v_mov_b32_e32 v70, v2
	v_mov_b32_e32 v71, v2
	v_mov_b32_e32 v72, v2
	v_mov_b32_e32 v73, v2
	v_mov_b32_e32 v82, v2
	v_mov_b32_e32 v83, v2
	v_mov_b32_e32 v84, v2
	v_mov_b32_e32 v85, v2
	v_mov_b32_e32 v86, v2
	v_mov_b32_e32 v87, v2
	v_mov_b32_e32 v88, v2
	v_mov_b32_e32 v89, v2
	v_mov_b32_e32 v98, v2
	v_mov_b32_e32 v99, v2
	v_mov_b32_e32 v100, v2
	v_mov_b32_e32 v101, v2
	v_mov_b32_e32 v102, v2
	v_mov_b32_e32 v103, v2
	v_mov_b32_e32 v104, v2
	v_mov_b32_e32 v105, v2
	v_mov_b32_e32 v114, v2
	v_mov_b32_e32 v115, v2
	v_mov_b32_e32 v116, v2
	v_mov_b32_e32 v117, v2
	v_mov_b32_e32 v118, v2
	v_mov_b32_e32 v119, v2
	v_mov_b32_e32 v120, v2
	v_mov_b32_e32 v121, v2
	v_mov_b32_e32 v74, v2
	v_mov_b32_e32 v75, v2
	v_mov_b32_e32 v76, v2
	v_mov_b32_e32 v77, v2
	v_mov_b32_e32 v78, v2
	v_mov_b32_e32 v79, v2
	v_mov_b32_e32 v80, v2
	v_mov_b32_e32 v81, v2
	v_mov_b32_e32 v90, v2
	v_mov_b32_e32 v91, v2
	v_mov_b32_e32 v92, v2
	v_mov_b32_e32 v93, v2
	v_mov_b32_e32 v94, v2
	v_mov_b32_e32 v95, v2
	v_mov_b32_e32 v96, v2
	v_mov_b32_e32 v97, v2
	v_mov_b32_e32 v106, v2
	v_mov_b32_e32 v107, v2
	v_mov_b32_e32 v108, v2
	v_mov_b32_e32 v109, v2
	v_mov_b32_e32 v110, v2
	v_mov_b32_e32 v111, v2
	v_mov_b32_e32 v112, v2
	v_mov_b32_e32 v113, v2
	v_mov_b32_e32 v122, v2
	v_mov_b32_e32 v123, v2
	v_mov_b32_e32 v124, v2
	v_mov_b32_e32 v125, v2
	v_mov_b32_e32 v126, v2
	v_mov_b32_e32 v127, v2
	v_mov_b32_e32 v128, v2
	v_mov_b32_e32 v129, v2
	s_add_i32 s86, 0, 0x10000
	v_add_u32_e32 v0, s86, v150
	ds_read_b128 v[142:145], v0
	ds_read_b128 v[146:149], v0 offset:1024
	ds_read_b128 v[152:155], v0 offset:2048
	ds_read_b128 v[156:159], v0 offset:3072
	s_add_u32 s12, s4, 0xfffc0080
	s_addc_u32 s13, s5, -1
	s_cmp_eq_u32 s85, 12
	s_cselect_b32 s15, s44, s13
	s_cselect_b32 s14, s45, s12
	s_cselect_b32 s13, s47, s79
	s_cselect_b32 s12, s55, s78
.LBB0_267:
	v_lshl_add_u64 v[194:195], s[4:5], 0, v[138:139]
	s_add_i32 m0, s7, 0xc000
	ds_read_b128 v[160:163], v151
	ds_read_b128 v[164:167], v151 offset:1024
	ds_read_b128 v[168:171], v151 offset:2048
	ds_read_b128 v[172:175], v151 offset:3072
	ds_read_b128 v[176:179], v151 offset:4096
	ds_read_b128 v[180:183], v151 offset:5120
	ds_read_b128 v[184:187], v151 offset:6144
	ds_read_b128 v[190:193], v151 offset:7168
	global_load_lds_dwordx4 v[194:195], off
	s_add_i32 m0, s7, 0xe000
	v_lshl_add_u64 v[194:195], s[4:5], 0, v[140:141]
	global_load_lds_dwordx4 v[194:195], off
	s_waitcnt lgkmcnt(8)
	s_barrier
	s_waitcnt lgkmcnt(0)
	v_mfma_f32_16x16x32_bf16 v[126:129], v[142:145], v[160:163], v[126:129]
	v_mfma_f32_16x16x32_bf16 v[122:125], v[152:155], v[160:163], v[122:125]
	v_mfma_f32_16x16x32_bf16 v[110:113], v[142:145], v[168:171], v[110:113]
	v_mfma_f32_16x16x32_bf16 v[106:109], v[152:155], v[168:171], v[106:109]
	v_mfma_f32_16x16x32_bf16 v[94:97], v[142:145], v[176:179], v[94:97]
	v_mfma_f32_16x16x32_bf16 v[90:93], v[152:155], v[176:179], v[90:93]
	v_mfma_f32_16x16x32_bf16 v[78:81], v[142:145], v[184:187], v[78:81]
	v_mfma_f32_16x16x32_bf16 v[74:77], v[152:155], v[184:187], v[74:77]
	v_mfma_f32_16x16x32_bf16 v[126:129], v[146:149], v[164:167], v[126:129]
	v_mfma_f32_16x16x32_bf16 v[122:125], v[156:159], v[164:167], v[122:125]
	v_mfma_f32_16x16x32_bf16 v[110:113], v[146:149], v[172:175], v[110:113]
	v_mfma_f32_16x16x32_bf16 v[106:109], v[156:159], v[172:175], v[106:109]
	v_mfma_f32_16x16x32_bf16 v[94:97], v[146:149], v[180:183], v[94:97]
	v_mfma_f32_16x16x32_bf16 v[90:93], v[156:159], v[180:183], v[90:93]
	v_mfma_f32_16x16x32_bf16 v[78:81], v[146:149], v[190:193], v[78:81]
	v_mfma_f32_16x16x32_bf16 v[74:77], v[156:159], v[190:193], v[74:77]
	s_barrier
	s_add_i32 s88, 0, 0x14000
	s_add_i32 s86, s86, s22
	v_add_u32_e32 v0, s88, v150
	v_lshl_add_u64 v[210:211], s[12:13], 0, v[134:135]
	s_mov_b32 m0, s86
	ds_read_b128 v[194:197], v0
	ds_read_b128 v[198:201], v0 offset:1024
	ds_read_b128 v[202:205], v0 offset:2048
	ds_read_b128 v[206:209], v0 offset:3072
	global_load_lds_dwordx4 v[210:211], off
	s_add_i32 m0, s86, 0x2000
	v_lshl_add_u64 v[212:213], s[12:13], 0, v[130:131]
	global_load_lds_dwordx4 v[212:213], off
	s_barrier
	s_waitcnt lgkmcnt(0)
	v_mfma_f32_16x16x32_bf16 v[118:121], v[194:197], v[160:163], v[118:121]
	v_mfma_f32_16x16x32_bf16 v[114:117], v[202:205], v[160:163], v[114:117]
	v_mfma_f32_16x16x32_bf16 v[102:105], v[194:197], v[168:171], v[102:105]
	v_mfma_f32_16x16x32_bf16 v[98:101], v[202:205], v[168:171], v[98:101]
	v_mfma_f32_16x16x32_bf16 v[86:89], v[194:197], v[176:179], v[86:89]
	v_mfma_f32_16x16x32_bf16 v[82:85], v[202:205], v[176:179], v[82:85]
	v_mfma_f32_16x16x32_bf16 v[70:73], v[194:197], v[184:187], v[70:73]
	v_mfma_f32_16x16x32_bf16 v[66:69], v[202:205], v[184:187], v[66:69]
	v_mfma_f32_16x16x32_bf16 v[118:121], v[198:201], v[164:167], v[118:121]
	v_mfma_f32_16x16x32_bf16 v[114:117], v[206:209], v[164:167], v[114:117]
	v_mfma_f32_16x16x32_bf16 v[102:105], v[198:201], v[172:175], v[102:105]
	v_mfma_f32_16x16x32_bf16 v[98:101], v[206:209], v[172:175], v[98:101]
	v_mfma_f32_16x16x32_bf16 v[86:89], v[198:201], v[180:183], v[86:89]
	v_mfma_f32_16x16x32_bf16 v[82:85], v[206:209], v[180:183], v[82:85]
	v_mfma_f32_16x16x32_bf16 v[70:73], v[198:201], v[190:193], v[70:73]
	v_mfma_f32_16x16x32_bf16 v[66:69], v[206:209], v[190:193], v[66:69]
	s_mov_b32 m0, s7
	v_lshl_add_u64 v[214:215], s[14:15], 0, v[136:137]
	s_barrier
	ds_read_b128 v[160:163], v151 offset:16384
	ds_read_b128 v[164:167], v151 offset:17408
	ds_read_b128 v[168:171], v151 offset:18432
	ds_read_b128 v[172:175], v151 offset:19456
	ds_read_b128 v[176:179], v151 offset:20480
	ds_read_b128 v[180:183], v151 offset:21504
	ds_read_b128 v[184:187], v151 offset:22528
	ds_read_b128 v[190:193], v151 offset:23552
	global_load_lds_dwordx4 v[214:215], off
	s_mov_b32 m0, s23
	v_lshl_add_u64 v[216:217], s[14:15], 0, v[132:133]
	global_load_lds_dwordx4 v[216:217], off
	s_waitcnt vmcnt(10)
	s_barrier
	s_waitcnt lgkmcnt(0)
	v_mfma_f32_16x16x32_bf16 v[62:65], v[142:145], v[160:163], v[62:65]
	v_mfma_f32_16x16x32_bf16 v[58:61], v[152:155], v[160:163], v[58:61]
	v_mfma_f32_16x16x32_bf16 v[46:49], v[142:145], v[168:171], v[46:49]
	v_mfma_f32_16x16x32_bf16 v[42:45], v[152:155], v[168:171], v[42:45]
	v_mfma_f32_16x16x32_bf16 v[30:33], v[142:145], v[176:179], v[30:33]
	v_mfma_f32_16x16x32_bf16 v[26:29], v[152:155], v[176:179], v[26:29]
	v_mfma_f32_16x16x32_bf16 v[14:17], v[142:145], v[184:187], v[14:17]
	v_mfma_f32_16x16x32_bf16 v[10:13], v[152:155], v[184:187], v[10:13]
	v_mfma_f32_16x16x32_bf16 v[62:65], v[146:149], v[164:167], v[62:65]
	v_mfma_f32_16x16x32_bf16 v[58:61], v[156:159], v[164:167], v[58:61]
	v_mfma_f32_16x16x32_bf16 v[46:49], v[146:149], v[172:175], v[46:49]
	v_mfma_f32_16x16x32_bf16 v[42:45], v[156:159], v[172:175], v[42:45]
	v_mfma_f32_16x16x32_bf16 v[30:33], v[146:149], v[180:183], v[30:33]
	v_mfma_f32_16x16x32_bf16 v[26:29], v[156:159], v[180:183], v[26:29]
	v_mfma_f32_16x16x32_bf16 v[14:17], v[146:149], v[190:193], v[14:17]
	v_mfma_f32_16x16x32_bf16 v[10:13], v[156:159], v[190:193], v[10:13]
	s_barrier
	s_add_u32 s86, s12, 0x40000
	s_addc_u32 s87, s13, 0
	s_add_i32 s88, s88, s22
	s_mov_b32 m0, s88
	v_lshl_add_u64 v[142:143], s[86:87], 0, v[134:135]
	global_load_lds_dwordx4 v[142:143], off
	s_add_i32 m0, s88, 0x2000
	v_lshl_add_u64 v[142:143], s[86:87], 0, v[130:131]
	global_load_lds_dwordx4 v[142:143], off
	s_add_i32 s86, 0, 0x18000
	v_add_u32_e32 v0, s86, v150
	ds_read_b128 v[142:145], v0
	ds_read_b128 v[146:149], v0 offset:1024
	ds_read_b128 v[152:155], v0 offset:2048
	ds_read_b128 v[156:159], v0 offset:3072
	s_waitcnt vmcnt(6)
	s_barrier
	v_mfma_f32_16x16x32_bf16 v[54:57], v[194:197], v[160:163], v[54:57]
	v_mfma_f32_16x16x32_bf16 v[50:53], v[202:205], v[160:163], v[50:53]
	v_mfma_f32_16x16x32_bf16 v[38:41], v[194:197], v[168:171], v[38:41]
	v_mfma_f32_16x16x32_bf16 v[34:37], v[202:205], v[168:171], v[34:37]
	v_mfma_f32_16x16x32_bf16 v[22:25], v[194:197], v[176:179], v[22:25]
	v_mfma_f32_16x16x32_bf16 v[18:21], v[202:205], v[176:179], v[18:21]
	v_mfma_f32_16x16x32_bf16 v[6:9], v[194:197], v[184:187], v[6:9]
	v_mfma_f32_16x16x32_bf16 v[2:5], v[202:205], v[184:187], v[2:5]
	v_mfma_f32_16x16x32_bf16 v[54:57], v[198:201], v[164:167], v[54:57]
	v_mfma_f32_16x16x32_bf16 v[50:53], v[206:209], v[164:167], v[50:53]
	v_mfma_f32_16x16x32_bf16 v[38:41], v[198:201], v[172:175], v[38:41]
	v_mfma_f32_16x16x32_bf16 v[34:37], v[206:209], v[172:175], v[34:37]
	v_mfma_f32_16x16x32_bf16 v[22:25], v[198:201], v[180:183], v[22:25]
	v_mfma_f32_16x16x32_bf16 v[18:21], v[206:209], v[180:183], v[18:21]
	v_mfma_f32_16x16x32_bf16 v[6:9], v[198:201], v[190:193], v[6:9]
	v_mfma_f32_16x16x32_bf16 v[2:5], v[206:209], v[190:193], v[2:5]
	s_barrier
	s_add_u32 s14, s14, 0x40000
	s_addc_u32 s15, s15, 0
	s_mov_b32 m0, s28
	v_lshl_add_u64 v[194:195], s[14:15], 0, v[136:137]
	ds_read_b128 v[160:163], v151 offset:32768
	ds_read_b128 v[164:167], v151 offset:33792
	ds_read_b128 v[168:171], v151 offset:34816
	ds_read_b128 v[172:175], v151 offset:35840
	ds_read_b128 v[176:179], v151 offset:36864
	ds_read_b128 v[180:183], v151 offset:37888
	ds_read_b128 v[184:187], v151 offset:38912
	ds_read_b128 v[190:193], v151 offset:39936
	global_load_lds_dwordx4 v[194:195], off
	s_mov_b32 m0, s29
	v_lshl_add_u64 v[194:195], s[14:15], 0, v[132:133]
	global_load_lds_dwordx4 v[194:195], off
	s_waitcnt lgkmcnt(8)
	s_barrier
	s_waitcnt lgkmcnt(0)
	v_mfma_f32_16x16x32_bf16 v[126:129], v[142:145], v[160:163], v[126:129]
	v_mfma_f32_16x16x32_bf16 v[122:125], v[152:155], v[160:163], v[122:125]
	v_mfma_f32_16x16x32_bf16 v[110:113], v[142:145], v[168:171], v[110:113]
	v_mfma_f32_16x16x32_bf16 v[106:109], v[152:155], v[168:171], v[106:109]
	v_mfma_f32_16x16x32_bf16 v[94:97], v[142:145], v[176:179], v[94:97]
	v_mfma_f32_16x16x32_bf16 v[90:93], v[152:155], v[176:179], v[90:93]
	v_mfma_f32_16x16x32_bf16 v[78:81], v[142:145], v[184:187], v[78:81]
	v_mfma_f32_16x16x32_bf16 v[74:77], v[152:155], v[184:187], v[74:77]
	v_mfma_f32_16x16x32_bf16 v[126:129], v[146:149], v[164:167], v[126:129]
	v_mfma_f32_16x16x32_bf16 v[122:125], v[156:159], v[164:167], v[122:125]
	v_mfma_f32_16x16x32_bf16 v[110:113], v[146:149], v[172:175], v[110:113]
	v_mfma_f32_16x16x32_bf16 v[106:109], v[156:159], v[172:175], v[106:109]
	v_mfma_f32_16x16x32_bf16 v[94:97], v[146:149], v[180:183], v[94:97]
	v_mfma_f32_16x16x32_bf16 v[90:93], v[156:159], v[180:183], v[90:93]
	v_mfma_f32_16x16x32_bf16 v[78:81], v[146:149], v[190:193], v[78:81]
	v_mfma_f32_16x16x32_bf16 v[74:77], v[156:159], v[190:193], v[74:77]
	s_barrier
	s_add_i32 s14, 0, 0x1c000
	s_add_i32 s15, s86, s22
	v_add_u32_e32 v0, s14, v150
	v_lshl_add_u64 v[210:211], v[210:211], 0, s[40:41]
	s_mov_b32 m0, s15
	ds_read_b128 v[194:197], v0
	ds_read_b128 v[198:201], v0 offset:1024
	ds_read_b128 v[202:205], v0 offset:2048
	ds_read_b128 v[206:209], v0 offset:3072
	global_load_lds_dwordx4 v[210:211], off
	s_add_i32 m0, s15, 0x2000
	v_lshl_add_u64 v[210:211], v[212:213], 0, s[40:41]
	global_load_lds_dwordx4 v[210:211], off
	s_barrier
	s_waitcnt lgkmcnt(0)
	v_mfma_f32_16x16x32_bf16 v[118:121], v[194:197], v[160:163], v[118:121]
	v_mfma_f32_16x16x32_bf16 v[114:117], v[202:205], v[160:163], v[114:117]
	v_mfma_f32_16x16x32_bf16 v[102:105], v[194:197], v[168:171], v[102:105]
	v_mfma_f32_16x16x32_bf16 v[98:101], v[202:205], v[168:171], v[98:101]
	v_mfma_f32_16x16x32_bf16 v[86:89], v[194:197], v[176:179], v[86:89]
	v_mfma_f32_16x16x32_bf16 v[82:85], v[202:205], v[176:179], v[82:85]
	v_mfma_f32_16x16x32_bf16 v[70:73], v[194:197], v[184:187], v[70:73]
	v_mfma_f32_16x16x32_bf16 v[66:69], v[202:205], v[184:187], v[66:69]
	v_mfma_f32_16x16x32_bf16 v[118:121], v[198:201], v[164:167], v[118:121]
	v_mfma_f32_16x16x32_bf16 v[114:117], v[206:209], v[164:167], v[114:117]
	v_mfma_f32_16x16x32_bf16 v[102:105], v[198:201], v[172:175], v[102:105]
	v_mfma_f32_16x16x32_bf16 v[98:101], v[206:209], v[172:175], v[98:101]
	v_mfma_f32_16x16x32_bf16 v[86:89], v[198:201], v[180:183], v[86:89]
	v_mfma_f32_16x16x32_bf16 v[82:85], v[206:209], v[180:183], v[82:85]
	v_mfma_f32_16x16x32_bf16 v[70:73], v[198:201], v[190:193], v[70:73]
	v_mfma_f32_16x16x32_bf16 v[66:69], v[206:209], v[190:193], v[66:69]
	s_mov_b32 m0, s38
	v_lshl_add_u64 v[210:211], v[214:215], 0, s[40:41]
	s_barrier
	ds_read_b128 v[160:163], v151 offset:49152
	ds_read_b128 v[164:167], v151 offset:50176
	ds_read_b128 v[168:171], v151 offset:51200
	ds_read_b128 v[172:175], v151 offset:52224
	ds_read_b128 v[176:179], v151 offset:53248
	ds_read_b128 v[180:183], v151 offset:54272
	ds_read_b128 v[184:187], v151 offset:55296
	ds_read_b128 v[190:193], v151 offset:56320
	global_load_lds_dwordx4 v[210:211], off
	s_mov_b32 m0, s39
	v_lshl_add_u64 v[210:211], v[216:217], 0, s[40:41]
	global_load_lds_dwordx4 v[210:211], off
	s_waitcnt vmcnt(10)
	s_barrier
	s_waitcnt lgkmcnt(0)
	v_mfma_f32_16x16x32_bf16 v[62:65], v[142:145], v[160:163], v[62:65]
	v_mfma_f32_16x16x32_bf16 v[58:61], v[152:155], v[160:163], v[58:61]
	v_mfma_f32_16x16x32_bf16 v[46:49], v[142:145], v[168:171], v[46:49]
	v_mfma_f32_16x16x32_bf16 v[42:45], v[152:155], v[168:171], v[42:45]
	v_mfma_f32_16x16x32_bf16 v[30:33], v[142:145], v[176:179], v[30:33]
	v_mfma_f32_16x16x32_bf16 v[26:29], v[152:155], v[176:179], v[26:29]
	v_mfma_f32_16x16x32_bf16 v[14:17], v[142:145], v[184:187], v[14:17]
	v_mfma_f32_16x16x32_bf16 v[10:13], v[152:155], v[184:187], v[10:13]
	v_mfma_f32_16x16x32_bf16 v[62:65], v[146:149], v[164:167], v[62:65]
	v_mfma_f32_16x16x32_bf16 v[58:61], v[156:159], v[164:167], v[58:61]
	v_mfma_f32_16x16x32_bf16 v[46:49], v[146:149], v[172:175], v[46:49]
	v_mfma_f32_16x16x32_bf16 v[42:45], v[156:159], v[172:175], v[42:45]
	v_mfma_f32_16x16x32_bf16 v[30:33], v[146:149], v[180:183], v[30:33]
	v_mfma_f32_16x16x32_bf16 v[26:29], v[156:159], v[180:183], v[26:29]
	v_mfma_f32_16x16x32_bf16 v[14:17], v[146:149], v[190:193], v[14:17]
	v_mfma_f32_16x16x32_bf16 v[10:13], v[156:159], v[190:193], v[10:13]
	s_barrier
	s_add_u32 s12, s12, 0x40080
	s_addc_u32 s13, s13, 0
	s_add_i32 s14, s14, s22
	s_mov_b32 m0, s14
	v_lshl_add_u64 v[142:143], s[12:13], 0, v[134:135]
	global_load_lds_dwordx4 v[142:143], off
	s_add_i32 m0, s14, 0x2000
	v_lshl_add_u64 v[142:143], s[12:13], 0, v[130:131]
	global_load_lds_dwordx4 v[142:143], off
	s_add_i32 s86, 0, 0x10000
	v_add_u32_e32 v0, s86, v150
	ds_read_b128 v[142:145], v0
	ds_read_b128 v[146:149], v0 offset:1024
	ds_read_b128 v[152:155], v0 offset:2048
	ds_read_b128 v[156:159], v0 offset:3072
	s_waitcnt vmcnt(6)
	s_barrier
	v_mfma_f32_16x16x32_bf16 v[54:57], v[194:197], v[160:163], v[54:57]
	v_mfma_f32_16x16x32_bf16 v[50:53], v[202:205], v[160:163], v[50:53]
	v_mfma_f32_16x16x32_bf16 v[38:41], v[194:197], v[168:171], v[38:41]
	v_mfma_f32_16x16x32_bf16 v[34:37], v[202:205], v[168:171], v[34:37]
	v_mfma_f32_16x16x32_bf16 v[22:25], v[194:197], v[176:179], v[22:25]
	v_mfma_f32_16x16x32_bf16 v[18:21], v[202:205], v[176:179], v[18:21]
	v_mfma_f32_16x16x32_bf16 v[6:9], v[194:197], v[184:187], v[6:9]
	v_mfma_f32_16x16x32_bf16 v[2:5], v[202:205], v[184:187], v[2:5]
	v_mfma_f32_16x16x32_bf16 v[54:57], v[198:201], v[164:167], v[54:57]
	v_mfma_f32_16x16x32_bf16 v[50:53], v[206:209], v[164:167], v[50:53]
	v_mfma_f32_16x16x32_bf16 v[38:41], v[198:201], v[172:175], v[38:41]
	v_mfma_f32_16x16x32_bf16 v[34:37], v[206:209], v[172:175], v[34:37]
	v_mfma_f32_16x16x32_bf16 v[22:25], v[198:201], v[180:183], v[22:25]
	v_mfma_f32_16x16x32_bf16 v[18:21], v[206:209], v[180:183], v[18:21]
	v_mfma_f32_16x16x32_bf16 v[6:9], v[198:201], v[190:193], v[6:9]
	v_mfma_f32_16x16x32_bf16 v[2:5], v[206:209], v[190:193], v[2:5]
	s_add_i32 s85, s85, 2
	s_add_u32 s4, s4, 0x100
	s_addc_u32 s5, s5, 0
	s_add_u32 s78, s78, 0x100
	s_addc_u32 s79, s79, 0
	s_add_u32 s12, s4, 0xfffc0080
	s_addc_u32 s13, s5, -1
	s_cmp_eq_u32 s85, 12
	s_cselect_b32 s15, s44, s13
	s_cselect_b32 s14, s45, s12
	s_cselect_b32 s13, s47, s79
	s_cselect_b32 s12, s55, s78
	s_cmp_gt_u32 s85, 13
	s_barrier
	s_cbranch_scc0 .LBB0_267
	s_waitcnt lgkmcnt(0)
	v_mov_b32_e32 v156, v252
	s_mov_b64 s[4:5], -1
	v_and_b32_e32 v154, 63, v156
	s_andn2_b64 vcc, exec, s[2:3]
	v_lshlrev_b32_e32 v142, 2, v154
	s_cbranch_vccnz .LBB0_270
	v_lshlrev_b32_e32 v155, 2, v154
	s_mov_b64 s[4:5], 0

.LBB0_837:
	s_ashr_i32 s15, s14, 31
	s_lshl_b64 s[78:79], s[14:15], 19
	s_add_u32 s84, s36, s78
	s_addc_u32 s85, s37, s79
	s_and_b64 s[4:5], s[4:5], exec
	s_cselect_b32 s15, s85, s91
	s_cselect_b32 s23, s84, s90
	s_add_u32 s34, s90, 0x100
	v_mov_b32_e32 v2, 0
	s_addc_u32 s75, s91, 0
	s_mov_b32 s78, -2
	s_waitcnt lgkmcnt(0)
	v_mov_b32_e32 v3, v2
	v_mov_b32_e32 v4, v2
	v_mov_b32_e32 v5, v2
	v_mov_b32_e32 v6, v2
	v_mov_b32_e32 v7, v2
	v_mov_b32_e32 v8, v2
	v_mov_b32_e32 v9, v2
	v_mov_b32_e32 v18, v2
	v_mov_b32_e32 v19, v2
	v_mov_b32_e32 v20, v2
	v_mov_b32_e32 v21, v2
	v_mov_b32_e32 v22, v2
	v_mov_b32_e32 v23, v2
	v_mov_b32_e32 v24, v2
	v_mov_b32_e32 v25, v2
	v_mov_b32_e32 v34, v2
	v_mov_b32_e32 v35, v2
	v_mov_b32_e32 v36, v2
	v_mov_b32_e32 v37, v2
	v_mov_b32_e32 v38, v2
	v_mov_b32_e32 v39, v2
	v_mov_b32_e32 v40, v2
	v_mov_b32_e32 v41, v2
	v_mov_b32_e32 v50, v2
	v_mov_b32_e32 v51, v2
	v_mov_b32_e32 v52, v2
	v_mov_b32_e32 v53, v2
	v_mov_b32_e32 v54, v2
	v_mov_b32_e32 v55, v2
	v_mov_b32_e32 v56, v2
	v_mov_b32_e32 v57, v2
	v_mov_b32_e32 v10, v2
	v_mov_b32_e32 v11, v2
	v_mov_b32_e32 v12, v2
	v_mov_b32_e32 v13, v2
	v_mov_b32_e32 v14, v2
	v_mov_b32_e32 v15, v2
	v_mov_b32_e32 v16, v2
	v_mov_b32_e32 v17, v2
	v_mov_b32_e32 v26, v2
	v_mov_b32_e32 v27, v2
	v_mov_b32_e32 v28, v2
	v_mov_b32_e32 v29, v2
	v_mov_b32_e32 v30, v2
	v_mov_b32_e32 v31, v2
	v_mov_b32_e32 v32, v2
	v_mov_b32_e32 v33, v2
	v_mov_b32_e32 v42, v2
	v_mov_b32_e32 v43, v2
	v_mov_b32_e32 v44, v2
	v_mov_b32_e32 v45, v2
	v_mov_b32_e32 v46, v2
	v_mov_b32_e32 v47, v2
	v_mov_b32_e32 v48, v2
	v_mov_b32_e32 v49, v2
	v_mov_b32_e32 v58, v2
	v_mov_b32_e32 v59, v2
	v_mov_b32_e32 v60, v2
	v_mov_b32_e32 v61, v2
	v_mov_b32_e32 v62, v2
	v_mov_b32_e32 v63, v2
	v_mov_b32_e32 v64, v2
	v_mov_b32_e32 v65, v2
	v_mov_b32_e32 v66, v2
	v_mov_b32_e32 v67, v2
	v_mov_b32_e32 v68, v2
	v_mov_b32_e32 v69, v2
	v_mov_b32_e32 v70, v2
	v_mov_b32_e32 v71, v2
	v_mov_b32_e32 v72, v2
	v_mov_b32_e32 v73, v2
	v_mov_b32_e32 v82, v2
	v_mov_b32_e32 v83, v2
	v_mov_b32_e32 v84, v2
	v_mov_b32_e32 v85, v2
	v_mov_b32_e32 v86, v2
	v_mov_b32_e32 v87, v2
	v_mov_b32_e32 v88, v2
	v_mov_b32_e32 v89, v2
	v_mov_b32_e32 v98, v2
	v_mov_b32_e32 v99, v2
	v_mov_b32_e32 v100, v2
	v_mov_b32_e32 v101, v2
	v_mov_b32_e32 v102, v2
	v_mov_b32_e32 v103, v2
	v_mov_b32_e32 v104, v2
	v_mov_b32_e32 v105, v2
	v_mov_b32_e32 v114, v2
	v_mov_b32_e32 v115, v2
	v_mov_b32_e32 v116, v2
	v_mov_b32_e32 v117, v2
	v_mov_b32_e32 v118, v2
	v_mov_b32_e32 v119, v2
	v_mov_b32_e32 v120, v2
	v_mov_b32_e32 v121, v2
	v_mov_b32_e32 v74, v2
	v_mov_b32_e32 v75, v2
	v_mov_b32_e32 v76, v2
	v_mov_b32_e32 v77, v2
	v_mov_b32_e32 v78, v2
	v_mov_b32_e32 v79, v2
	v_mov_b32_e32 v80, v2
	v_mov_b32_e32 v81, v2
	v_mov_b32_e32 v90, v2
	v_mov_b32_e32 v91, v2
	v_mov_b32_e32 v92, v2
	v_mov_b32_e32 v93, v2
	v_mov_b32_e32 v94, v2
	v_mov_b32_e32 v95, v2
	v_mov_b32_e32 v96, v2
	v_mov_b32_e32 v97, v2
	v_mov_b32_e32 v106, v2
	v_mov_b32_e32 v107, v2
	v_mov_b32_e32 v108, v2
	v_mov_b32_e32 v109, v2
	v_mov_b32_e32 v110, v2
	v_mov_b32_e32 v111, v2
	v_mov_b32_e32 v112, v2
	v_mov_b32_e32 v113, v2
	v_mov_b32_e32 v122, v2
	v_mov_b32_e32 v123, v2
	v_mov_b32_e32 v124, v2
	v_mov_b32_e32 v125, v2
	v_mov_b32_e32 v126, v2
	v_mov_b32_e32 v127, v2
	v_mov_b32_e32 v128, v2
	v_mov_b32_e32 v129, v2
	s_add_i32 s79, 0, 0x10000
	v_add_u32_e32 v142, s79, v212
	ds_read_b128 v[130:133], v142
	ds_read_b128 v[134:137], v142 offset:1024
	ds_read_b128 v[138:141], v142 offset:2048
	ds_read_b128 v[142:145], v142 offset:3072
	s_add_u32 s4, s88, 0x100
	s_addc_u32 s5, s89, 0
	s_cmp_eq_u32 s78, 12
	s_cselect_b32 s93, s17, s5
	s_cselect_b32 s92, s16, s4
	s_cselect_b32 s91, s15, s75
	s_cselect_b32 s90, s23, s34
.LBB0_838:
	v_lshl_add_u64 v[178:179], s[88:89], 0, v[196:197]
	s_add_i32 m0, s39, 0xc000
	ds_read_b128 v[146:149], v213
	ds_read_b128 v[150:153], v213 offset:1024
	ds_read_b128 v[154:157], v213 offset:2048
	ds_read_b128 v[158:161], v213 offset:3072
	ds_read_b128 v[162:165], v213 offset:4096
	ds_read_b128 v[166:169], v213 offset:5120
	ds_read_b128 v[170:173], v213 offset:6144
	ds_read_b128 v[174:177], v213 offset:7168
	global_load_lds_dwordx4 v[178:179], off
	s_add_i32 m0, s39, 0xe000
	v_lshl_add_u64 v[178:179], s[88:89], 0, v[198:199]
	global_load_lds_dwordx4 v[178:179], off
	s_waitcnt lgkmcnt(8)
	s_barrier
	s_waitcnt lgkmcnt(0)
	v_mfma_f32_16x16x32_bf16 v[126:129], v[130:133], v[146:149], v[126:129]
	v_mfma_f32_16x16x32_bf16 v[122:125], v[138:141], v[146:149], v[122:125]
	v_mfma_f32_16x16x32_bf16 v[110:113], v[130:133], v[154:157], v[110:113]
	v_mfma_f32_16x16x32_bf16 v[106:109], v[138:141], v[154:157], v[106:109]
	v_mfma_f32_16x16x32_bf16 v[94:97], v[130:133], v[162:165], v[94:97]
	v_mfma_f32_16x16x32_bf16 v[90:93], v[138:141], v[162:165], v[90:93]
	v_mfma_f32_16x16x32_bf16 v[78:81], v[130:133], v[170:173], v[78:81]
	v_mfma_f32_16x16x32_bf16 v[74:77], v[138:141], v[170:173], v[74:77]
	v_mfma_f32_16x16x32_bf16 v[126:129], v[134:137], v[150:153], v[126:129]
	v_mfma_f32_16x16x32_bf16 v[122:125], v[142:145], v[150:153], v[122:125]
	v_mfma_f32_16x16x32_bf16 v[110:113], v[134:137], v[158:161], v[110:113]
	v_mfma_f32_16x16x32_bf16 v[106:109], v[142:145], v[158:161], v[106:109]
	v_mfma_f32_16x16x32_bf16 v[94:97], v[134:137], v[166:169], v[94:97]
	v_mfma_f32_16x16x32_bf16 v[90:93], v[142:145], v[166:169], v[90:93]
	v_mfma_f32_16x16x32_bf16 v[78:81], v[134:137], v[174:177], v[78:81]
	v_mfma_f32_16x16x32_bf16 v[74:77], v[142:145], v[174:177], v[74:77]
	s_barrier
	s_add_i32 s87, 0, 0x14000
	v_add_u32_e32 v186, s87, v212
	s_add_i32 s79, s79, s38
	ds_read_b128 v[178:181], v186
	ds_read_b128 v[182:185], v186 offset:1024
	ds_read_b128 v[200:203], v186 offset:2048
	ds_read_b128 v[204:207], v186 offset:3072
	v_lshl_add_u64 v[186:187], s[90:91], 0, v[0:1]
	s_mov_b32 m0, s79
	v_lshl_add_u64 v[208:209], s[90:91], 0, v[194:195]
	global_load_lds_dwordx4 v[186:187], off
	s_add_i32 m0, s79, 0x2000
	s_nop 0
	global_load_lds_dwordx4 v[208:209], off
	s_barrier
	s_waitcnt lgkmcnt(0)
	v_mfma_f32_16x16x32_bf16 v[118:121], v[178:181], v[146:149], v[118:121]
	v_mfma_f32_16x16x32_bf16 v[114:117], v[200:203], v[146:149], v[114:117]
	v_mfma_f32_16x16x32_bf16 v[102:105], v[178:181], v[154:157], v[102:105]
	v_mfma_f32_16x16x32_bf16 v[98:101], v[200:203], v[154:157], v[98:101]
	v_mfma_f32_16x16x32_bf16 v[86:89], v[178:181], v[162:165], v[86:89]
	v_mfma_f32_16x16x32_bf16 v[82:85], v[200:203], v[162:165], v[82:85]
	v_mfma_f32_16x16x32_bf16 v[70:73], v[178:181], v[170:173], v[70:73]
	v_mfma_f32_16x16x32_bf16 v[66:69], v[200:203], v[170:173], v[66:69]
	v_mfma_f32_16x16x32_bf16 v[118:121], v[182:185], v[150:153], v[118:121]
	v_mfma_f32_16x16x32_bf16 v[114:117], v[204:207], v[150:153], v[114:117]
	v_mfma_f32_16x16x32_bf16 v[102:105], v[182:185], v[158:161], v[102:105]
	v_mfma_f32_16x16x32_bf16 v[98:101], v[204:207], v[158:161], v[98:101]
	v_mfma_f32_16x16x32_bf16 v[86:89], v[182:185], v[166:169], v[86:89]
	v_mfma_f32_16x16x32_bf16 v[82:85], v[204:207], v[166:169], v[82:85]
	v_mfma_f32_16x16x32_bf16 v[70:73], v[182:185], v[174:177], v[70:73]
	v_mfma_f32_16x16x32_bf16 v[66:69], v[204:207], v[174:177], v[66:69]
	s_mov_b32 m0, s39
	v_lshl_add_u64 v[210:211], s[92:93], 0, v[190:191]
	s_barrier
	ds_read_b128 v[146:149], v213 offset:16384
	ds_read_b128 v[150:153], v213 offset:17408
	ds_read_b128 v[154:157], v213 offset:18432
	ds_read_b128 v[158:161], v213 offset:19456
	ds_read_b128 v[162:165], v213 offset:20480
	ds_read_b128 v[166:169], v213 offset:21504
	ds_read_b128 v[170:173], v213 offset:22528
	ds_read_b128 v[174:177], v213 offset:23552
	global_load_lds_dwordx4 v[210:211], off
	s_mov_b32 m0, s42
	v_lshl_add_u64 v[214:215], s[92:93], 0, v[192:193]
	global_load_lds_dwordx4 v[214:215], off
	s_waitcnt vmcnt(10)
	s_barrier
	s_waitcnt lgkmcnt(0)
	v_mfma_f32_16x16x32_bf16 v[62:65], v[130:133], v[146:149], v[62:65]
	v_mfma_f32_16x16x32_bf16 v[58:61], v[138:141], v[146:149], v[58:61]
	v_mfma_f32_16x16x32_bf16 v[46:49], v[130:133], v[154:157], v[46:49]
	v_mfma_f32_16x16x32_bf16 v[42:45], v[138:141], v[154:157], v[42:45]
	v_mfma_f32_16x16x32_bf16 v[30:33], v[130:133], v[162:165], v[30:33]
	v_mfma_f32_16x16x32_bf16 v[26:29], v[138:141], v[162:165], v[26:29]
	v_mfma_f32_16x16x32_bf16 v[14:17], v[130:133], v[170:173], v[14:17]
	v_mfma_f32_16x16x32_bf16 v[10:13], v[138:141], v[170:173], v[10:13]
	v_mfma_f32_16x16x32_bf16 v[62:65], v[134:137], v[150:153], v[62:65]
	v_mfma_f32_16x16x32_bf16 v[58:61], v[142:145], v[150:153], v[58:61]
	v_mfma_f32_16x16x32_bf16 v[46:49], v[134:137], v[158:161], v[46:49]
	v_mfma_f32_16x16x32_bf16 v[42:45], v[142:145], v[158:161], v[42:45]
	v_mfma_f32_16x16x32_bf16 v[30:33], v[134:137], v[166:169], v[30:33]
	v_mfma_f32_16x16x32_bf16 v[26:29], v[142:145], v[166:169], v[26:29]
	v_mfma_f32_16x16x32_bf16 v[14:17], v[134:137], v[174:177], v[14:17]
	v_mfma_f32_16x16x32_bf16 v[10:13], v[142:145], v[174:177], v[10:13]
	s_barrier
	s_add_u32 s88, s90, 0x40000
	s_addc_u32 s89, s91, 0
	s_add_i32 s79, s87, s38
	s_mov_b32 m0, s79
	v_lshl_add_u64 v[130:131], s[88:89], 0, v[0:1]
	global_load_lds_dwordx4 v[130:131], off
	s_add_i32 m0, s79, 0x2000
	v_lshl_add_u64 v[130:131], s[88:89], 0, v[194:195]
	global_load_lds_dwordx4 v[130:131], off
	s_add_i32 s79, 0, 0x18000
	v_add_u32_e32 v142, s79, v212
	ds_read_b128 v[130:133], v142
	ds_read_b128 v[134:137], v142 offset:1024
	ds_read_b128 v[138:141], v142 offset:2048
	ds_read_b128 v[142:145], v142 offset:3072
	s_waitcnt vmcnt(6)
	s_barrier
	v_mfma_f32_16x16x32_bf16 v[54:57], v[178:181], v[146:149], v[54:57]
	v_mfma_f32_16x16x32_bf16 v[50:53], v[200:203], v[146:149], v[50:53]
	v_mfma_f32_16x16x32_bf16 v[38:41], v[178:181], v[154:157], v[38:41]
	v_mfma_f32_16x16x32_bf16 v[34:37], v[200:203], v[154:157], v[34:37]
	v_mfma_f32_16x16x32_bf16 v[22:25], v[178:181], v[162:165], v[22:25]
	v_mfma_f32_16x16x32_bf16 v[18:21], v[200:203], v[162:165], v[18:21]
	v_mfma_f32_16x16x32_bf16 v[6:9], v[178:181], v[170:173], v[6:9]
	v_mfma_f32_16x16x32_bf16 v[2:5], v[200:203], v[170:173], v[2:5]
	v_mfma_f32_16x16x32_bf16 v[54:57], v[182:185], v[150:153], v[54:57]
	v_mfma_f32_16x16x32_bf16 v[50:53], v[204:207], v[150:153], v[50:53]
	v_mfma_f32_16x16x32_bf16 v[38:41], v[182:185], v[158:161], v[38:41]
	v_mfma_f32_16x16x32_bf16 v[34:37], v[204:207], v[158:161], v[34:37]
	v_mfma_f32_16x16x32_bf16 v[22:25], v[182:185], v[166:169], v[22:25]
	v_mfma_f32_16x16x32_bf16 v[18:21], v[204:207], v[166:169], v[18:21]
	v_mfma_f32_16x16x32_bf16 v[6:9], v[182:185], v[174:177], v[6:9]
	v_mfma_f32_16x16x32_bf16 v[2:5], v[204:207], v[174:177], v[2:5]
	s_barrier
	s_add_u32 s88, s92, 0xc0000
	s_addc_u32 s89, s93, 0
	s_mov_b32 m0, s43
	v_lshl_add_u64 v[178:179], s[88:89], 0, v[190:191]
	ds_read_b128 v[146:149], v213 offset:32768
	ds_read_b128 v[150:153], v213 offset:33792
	ds_read_b128 v[154:157], v213 offset:34816
	ds_read_b128 v[158:161], v213 offset:35840
	ds_read_b128 v[162:165], v213 offset:36864
	ds_read_b128 v[166:169], v213 offset:37888
	ds_read_b128 v[170:173], v213 offset:38912
	ds_read_b128 v[174:177], v213 offset:39936
	global_load_lds_dwordx4 v[178:179], off
	s_mov_b32 m0, s44
	v_lshl_add_u64 v[178:179], s[88:89], 0, v[192:193]
	global_load_lds_dwordx4 v[178:179], off
	s_waitcnt lgkmcnt(8)
	s_barrier
	s_waitcnt lgkmcnt(0)
	v_mfma_f32_16x16x32_bf16 v[126:129], v[130:133], v[146:149], v[126:129]
	v_mfma_f32_16x16x32_bf16 v[122:125], v[138:141], v[146:149], v[122:125]
	v_mfma_f32_16x16x32_bf16 v[110:113], v[130:133], v[154:157], v[110:113]
	v_mfma_f32_16x16x32_bf16 v[106:109], v[138:141], v[154:157], v[106:109]
	v_mfma_f32_16x16x32_bf16 v[94:97], v[130:133], v[162:165], v[94:97]
	v_mfma_f32_16x16x32_bf16 v[90:93], v[138:141], v[162:165], v[90:93]
	v_mfma_f32_16x16x32_bf16 v[78:81], v[130:133], v[170:173], v[78:81]
	v_mfma_f32_16x16x32_bf16 v[74:77], v[138:141], v[170:173], v[74:77]
	v_mfma_f32_16x16x32_bf16 v[126:129], v[134:137], v[150:153], v[126:129]
	v_mfma_f32_16x16x32_bf16 v[122:125], v[142:145], v[150:153], v[122:125]
	v_mfma_f32_16x16x32_bf16 v[110:113], v[134:137], v[158:161], v[110:113]
	v_mfma_f32_16x16x32_bf16 v[106:109], v[142:145], v[158:161], v[106:109]
	v_mfma_f32_16x16x32_bf16 v[94:97], v[134:137], v[166:169], v[94:97]
	v_mfma_f32_16x16x32_bf16 v[90:93], v[142:145], v[166:169], v[90:93]
	v_mfma_f32_16x16x32_bf16 v[78:81], v[134:137], v[174:177], v[78:81]
	v_mfma_f32_16x16x32_bf16 v[74:77], v[142:145], v[174:177], v[74:77]
	s_barrier
	s_add_i32 s87, 0, 0x1c000
	s_add_i32 s79, s79, s38
	v_add_u32_e32 v204, s87, v212
	v_lshl_add_u64 v[186:187], v[186:187], 0, s[40:41]
	s_mov_b32 m0, s79
	ds_read_b128 v[178:181], v204
	ds_read_b128 v[182:185], v204 offset:1024
	ds_read_b128 v[200:203], v204 offset:2048
	ds_read_b128 v[204:207], v204 offset:3072
	global_load_lds_dwordx4 v[186:187], off
	s_add_i32 m0, s79, 0x2000
	v_lshl_add_u64 v[186:187], v[208:209], 0, s[40:41]
	global_load_lds_dwordx4 v[186:187], off
	s_barrier
	s_waitcnt lgkmcnt(0)
	v_mfma_f32_16x16x32_bf16 v[118:121], v[178:181], v[146:149], v[118:121]
	v_mfma_f32_16x16x32_bf16 v[114:117], v[200:203], v[146:149], v[114:117]
	v_mfma_f32_16x16x32_bf16 v[102:105], v[178:181], v[154:157], v[102:105]
	v_mfma_f32_16x16x32_bf16 v[98:101], v[200:203], v[154:157], v[98:101]
	v_mfma_f32_16x16x32_bf16 v[86:89], v[178:181], v[162:165], v[86:89]
	v_mfma_f32_16x16x32_bf16 v[82:85], v[200:203], v[162:165], v[82:85]
	v_mfma_f32_16x16x32_bf16 v[70:73], v[178:181], v[170:173], v[70:73]
	v_mfma_f32_16x16x32_bf16 v[66:69], v[200:203], v[170:173], v[66:69]
	v_mfma_f32_16x16x32_bf16 v[118:121], v[182:185], v[150:153], v[118:121]
	v_mfma_f32_16x16x32_bf16 v[114:117], v[204:207], v[150:153], v[114:117]
	v_mfma_f32_16x16x32_bf16 v[102:105], v[182:185], v[158:161], v[102:105]
	v_mfma_f32_16x16x32_bf16 v[98:101], v[204:207], v[158:161], v[98:101]
	v_mfma_f32_16x16x32_bf16 v[86:89], v[182:185], v[166:169], v[86:89]
	v_mfma_f32_16x16x32_bf16 v[82:85], v[204:207], v[166:169], v[82:85]
	v_mfma_f32_16x16x32_bf16 v[70:73], v[182:185], v[174:177], v[70:73]
	v_mfma_f32_16x16x32_bf16 v[66:69], v[204:207], v[174:177], v[66:69]
	s_mov_b32 m0, s60
	v_lshl_add_u64 v[186:187], v[210:211], 0, s[40:41]
	s_barrier
	ds_read_b128 v[146:149], v213 offset:49152
	ds_read_b128 v[150:153], v213 offset:50176
	ds_read_b128 v[154:157], v213 offset:51200
	ds_read_b128 v[158:161], v213 offset:52224
	ds_read_b128 v[162:165], v213 offset:53248
	ds_read_b128 v[166:169], v213 offset:54272
	ds_read_b128 v[170:173], v213 offset:55296
	ds_read_b128 v[174:177], v213 offset:56320
	global_load_lds_dwordx4 v[186:187], off
	s_mov_b32 m0, s61
	v_lshl_add_u64 v[186:187], v[214:215], 0, s[40:41]
	global_load_lds_dwordx4 v[186:187], off
	s_waitcnt vmcnt(10)
	s_barrier
	s_waitcnt lgkmcnt(0)
	v_mfma_f32_16x16x32_bf16 v[62:65], v[130:133], v[146:149], v[62:65]
	v_mfma_f32_16x16x32_bf16 v[58:61], v[138:141], v[146:149], v[58:61]
	v_mfma_f32_16x16x32_bf16 v[46:49], v[130:133], v[154:157], v[46:49]
	v_mfma_f32_16x16x32_bf16 v[42:45], v[138:141], v[154:157], v[42:45]
	v_mfma_f32_16x16x32_bf16 v[30:33], v[130:133], v[162:165], v[30:33]
	v_mfma_f32_16x16x32_bf16 v[26:29], v[138:141], v[162:165], v[26:29]
	v_mfma_f32_16x16x32_bf16 v[14:17], v[130:133], v[170:173], v[14:17]
	v_mfma_f32_16x16x32_bf16 v[10:13], v[138:141], v[170:173], v[10:13]
	v_mfma_f32_16x16x32_bf16 v[62:65], v[134:137], v[150:153], v[62:65]
	v_mfma_f32_16x16x32_bf16 v[58:61], v[142:145], v[150:153], v[58:61]
	v_mfma_f32_16x16x32_bf16 v[46:49], v[134:137], v[158:161], v[46:49]
	v_mfma_f32_16x16x32_bf16 v[42:45], v[142:145], v[158:161], v[42:45]
	v_mfma_f32_16x16x32_bf16 v[30:33], v[134:137], v[166:169], v[30:33]
	v_mfma_f32_16x16x32_bf16 v[26:29], v[142:145], v[166:169], v[26:29]
	v_mfma_f32_16x16x32_bf16 v[14:17], v[134:137], v[174:177], v[14:17]
	v_mfma_f32_16x16x32_bf16 v[10:13], v[142:145], v[174:177], v[10:13]
	s_barrier
	s_add_u32 s88, s90, 0x40080
	s_addc_u32 s89, s91, 0
	s_add_i32 s79, s87, s38
	s_mov_b32 m0, s79
	v_lshl_add_u64 v[130:131], s[88:89], 0, v[0:1]
	global_load_lds_dwordx4 v[130:131], off
	s_add_i32 m0, s79, 0x2000
	v_lshl_add_u64 v[130:131], s[88:89], 0, v[194:195]
	global_load_lds_dwordx4 v[130:131], off
	s_add_i32 s79, 0, 0x10000
	v_add_u32_e32 v142, s79, v212
	ds_read_b128 v[130:133], v142
	ds_read_b128 v[134:137], v142 offset:1024
	ds_read_b128 v[138:141], v142 offset:2048
	ds_read_b128 v[142:145], v142 offset:3072
	s_waitcnt vmcnt(6)
	s_barrier
	v_mfma_f32_16x16x32_bf16 v[54:57], v[178:181], v[146:149], v[54:57]
	v_mfma_f32_16x16x32_bf16 v[50:53], v[200:203], v[146:149], v[50:53]
	v_mfma_f32_16x16x32_bf16 v[38:41], v[178:181], v[154:157], v[38:41]
	v_mfma_f32_16x16x32_bf16 v[34:37], v[200:203], v[154:157], v[34:37]
	v_mfma_f32_16x16x32_bf16 v[22:25], v[178:181], v[162:165], v[22:25]
	v_mfma_f32_16x16x32_bf16 v[18:21], v[200:203], v[162:165], v[18:21]
	v_mfma_f32_16x16x32_bf16 v[6:9], v[178:181], v[170:173], v[6:9]
	v_mfma_f32_16x16x32_bf16 v[2:5], v[200:203], v[170:173], v[2:5]
	v_mfma_f32_16x16x32_bf16 v[54:57], v[182:185], v[150:153], v[54:57]
	v_mfma_f32_16x16x32_bf16 v[50:53], v[204:207], v[150:153], v[50:53]
	v_mfma_f32_16x16x32_bf16 v[38:41], v[182:185], v[158:161], v[38:41]
	v_mfma_f32_16x16x32_bf16 v[34:37], v[204:207], v[158:161], v[34:37]
	v_mfma_f32_16x16x32_bf16 v[22:25], v[182:185], v[166:169], v[22:25]
	v_mfma_f32_16x16x32_bf16 v[18:21], v[204:207], v[166:169], v[18:21]
	v_mfma_f32_16x16x32_bf16 v[6:9], v[182:185], v[174:177], v[6:9]
	v_mfma_f32_16x16x32_bf16 v[2:5], v[204:207], v[174:177], v[2:5]
	s_add_i32 s78, s78, 2
	s_add_u32 s34, s34, 0x100
	s_addc_u32 s75, s75, 0
	s_mov_b64 s[88:89], s[4:5]
	s_add_u32 s4, s88, 0x100
	s_addc_u32 s5, s89, 0
	s_cmp_eq_u32 s78, 12
	s_cselect_b32 s93, s17, s5
	s_cselect_b32 s92, s16, s4
	s_cselect_b32 s91, s15, s75
	s_cselect_b32 s90, s23, s34
	s_cmp_gt_u32 s78, 13
	s_barrier
	s_cbranch_scc0 .LBB0_838
	s_waitcnt lgkmcnt(0)
	s_lshl_b32 s4, s22, 8
	v_mov_b32_e32 v186, v252
	s_add_i32 s4, s4, s47
	s_nop 0
	v_and_or_b32 v202, v186, 15, s4
	s_lshl_b32 s4, s86, 8
	s_or_b32 s4, s4, s55
	v_lshrrev_b32_e32 v130, 1, v186
	v_and_or_b32 v200, v130, 24, s4
	v_ashrrev_i32_e32 v201, 31, v200
	v_ashrrev_i32_e32 v203, 31, v202
	v_lshl_add_u64 v[204:205], v[200:201], 2, s[6:7]
	v_lshlrev_b64 v[130:131], 12, v[202:203]
	v_lshl_add_u64 v[130:131], v[204:205], 0, v[130:131]
	global_load_dwordx4 v[216:219], v[130:131], off offset:16
	global_load_dwordx4 v[220:223], v[130:131], off
	global_load_dwordx4 v[178:181], v[130:131], off offset:528
	global_load_dwordx4 v[182:185], v[130:131], off offset:512
	v_or_b32_e32 v210, 16, v202
	v_ashrrev_i32_e32 v211, 31, v210
	v_lshlrev_b64 v[130:131], 12, v[210:211]
	v_or_b32_e32 v208, 32, v202
	v_lshl_add_u64 v[130:131], v[204:205], 0, v[130:131]
	v_ashrrev_i32_e32 v209, 31, v208
	global_load_dwordx4 v[170:173], v[130:131], off offset:16
	global_load_dwordx4 v[174:177], v[130:131], off
	global_load_dwordx4 v[162:165], v[130:131], off offset:528
	global_load_dwordx4 v[166:169], v[130:131], off offset:512
	v_lshlrev_b64 v[130:131], 12, v[208:209]
	v_or_b32_e32 v206, 48, v202
	v_lshl_add_u64 v[130:131], v[204:205], 0, v[130:131]
	v_ashrrev_i32_e32 v207, 31, v206
	global_load_dwordx4 v[154:157], v[130:131], off offset:16
	global_load_dwordx4 v[158:161], v[130:131], off
	global_load_dwordx4 v[138:141], v[130:131], off offset:528
	global_load_dwordx4 v[142:145], v[130:131], off offset:512
	v_lshlrev_b64 v[130:131], 12, v[206:207]
	v_lshl_add_u64 v[134:135], v[204:205], 0, v[130:131]
	global_load_dwordx4 v[146:149], v[134:135], off offset:16
	global_load_dwordx4 v[150:153], v[134:135], off
	global_load_dwordx4 v[130:133], v[134:135], off offset:528
	s_nop 0
	global_load_dwordx4 v[134:137], v[134:135], off offset:512
	v_and_b32_e32 v186, 63, v186
	v_lshlrev_b32_e32 v187, 2, v186
	v_xor_b32_e32 v215, 64, v187
	v_xor_b32_e32 v214, 0x80, v187
	v_cmp_gt_u32_e32 vcc, 16, v186
	v_lshlrev_b64 v[186:187], 10, v[202:203]
	v_lshl_add_u64 v[186:187], v[186:187], 0, v[200:201]
	s_lshl_b32 s4, s86, 2
	s_ashr_i32 s5, s4, 31
	s_waitcnt vmcnt(0)
	v_pk_add_f32 v[124:125], v[124:125], v[218:219]
	v_pk_add_f32 v[128:129], v[128:129], v[222:223]
	v_pk_add_f32 v[126:127], v[126:127], v[220:221]
	v_pk_mul_f32 v[218:219], v[128:129], v[128:129]
	v_pk_mul_f32 v[220:221], v[126:127], v[126:127]
	v_pk_add_f32 v[122:123], v[122:123], v[216:217]
	v_lshl_add_u64 v[216:217], v[186:187], 2, s[12:13]
	v_add_f32_e32 v220, v220, v221
	v_add_f32_e32 v218, v218, v219
	global_store_dwordx4 v[216:217], v[126:129], off
	global_store_dwordx4 v[216:217], v[122:125], off offset:16
	v_add_f32_e32 v222, v220, v218
	v_pk_mul_f32 v[220:221], v[122:123], v[122:123]
	v_cvt_pk_bf16_f32 v126, v126, v127
	v_cvt_pk_bf16_f32 v127, v128, v129
	v_cvt_pk_bf16_f32 v128, v122, v123
	v_cvt_pk_bf16_f32 v129, v124, v125
	v_lshl_add_u64 v[122:123], v[186:187], 1, s[8:9]
	v_pk_add_f32 v[120:121], v[120:121], v[184:185]
	v_pk_add_f32 v[118:119], v[118:119], v[182:183]
	v_pk_mul_f32 v[218:219], v[124:125], v[124:125]
	global_store_dwordx4 v[122:123], v[126:129], off
	v_pk_mul_f32 v[124:125], v[120:121], v[120:121]
	v_pk_add_f32 v[116:117], v[116:117], v[180:181]
	v_pk_mul_f32 v[126:127], v[118:119], v[118:119]
	v_pk_add_f32 v[114:115], v[114:115], v[178:179]
	v_add_f32_e32 v126, v126, v127
	v_add_f32_e32 v124, v124, v125
	v_add_f32_e32 v128, v126, v124
	v_pk_mul_f32 v[124:125], v[116:117], v[116:117]
	v_pk_mul_f32 v[126:127], v[114:115], v[114:115]
	v_add_f32_e32 v220, v220, v221
	v_add_f32_e32 v218, v218, v219
	v_add_f32_e32 v126, v126, v127
	v_add_f32_e32 v124, v124, v125
	v_add_f32_e32 v218, v220, v218
	v_add_f32_e32 v124, v126, v124
	v_add_f32_e32 v218, v222, v218
	v_add_f32_e32 v124, v128, v124
	v_add_f32_e32 v124, v218, v124
	global_store_dwordx4 v[216:217], v[118:121], off offset:512
	global_store_dwordx4 v[216:217], v[114:117], off offset:528
	s_nop 0
	v_cvt_pk_bf16_f32 v118, v118, v119
	v_cvt_pk_bf16_f32 v119, v120, v121
	v_cvt_pk_bf16_f32 v120, v114, v115
	ds_bpermute_b32 v114, v215, v124
	v_cvt_pk_bf16_f32 v121, v116, v117
	global_store_dwordx4 v[122:123], v[118:121], off offset:256
	s_waitcnt lgkmcnt(0)
	v_add_f32_e32 v114, v124, v114
	ds_bpermute_b32 v115, v214, v114
	s_and_saveexec_b64 s[22:23], vcc
	s_cbranch_execz .LBB0_841
	v_lshlrev_b64 v[116:117], 6, v[202:203]
	v_lshl_add_u64 v[116:117], s[10:11], 0, v[116:117]
	v_lshl_add_u64 v[116:117], s[4:5], 2, v[116:117]
	s_lshl_b32 s34, s45, 2
	v_lshl_add_u64 v[116:117], v[116:117], 0, s[34:35]
	s_waitcnt lgkmcnt(0)
	v_add_f32_e32 v114, v114, v115
	global_store_dword v[116:117], v114, off

.LBB0_918:
	s_ashr_i32 s17, s16, 31
	s_lshl_b64 s[22:23], s[16:17], 19
	v_mov_b64_e32 v[2:3], 0xb00
	s_add_u32 s84, s8, s22
	v_cmp_lt_i64_e32 vcc, s[28:29], v[2:3]
	s_addc_u32 s85, s9, s23
	s_and_b64 s[22:23], vcc, exec
	s_cselect_b32 s17, s85, s7
	s_cselect_b32 s22, s84, s6
	s_ashr_i32 s15, s14, 31
	s_lshl_b64 s[28:29], s[14:15], 19
	s_add_u32 s86, s37, s28
	s_addc_u32 s87, s38, s29
	s_and_b64 s[28:29], vcc, exec
	s_cselect_b32 s15, s87, s89
	s_cselect_b32 s23, s86, s88
	s_add_u32 s28, s88, 0x100
	v_mov_b32_e32 v70, 0
	s_addc_u32 s29, s89, 0
	s_mov_b32 s45, -2
	v_mov_b32_e32 v71, v70
	v_mov_b32_e32 v72, v70
	v_mov_b32_e32 v73, v70
	v_mov_b32_e32 v74, v70
	v_mov_b32_e32 v75, v70
	v_mov_b32_e32 v76, v70
	v_mov_b32_e32 v77, v70
	v_mov_b32_e32 v66, v70
	v_mov_b32_e32 v67, v70
	v_mov_b32_e32 v68, v70
	v_mov_b32_e32 v69, v70
	v_mov_b32_e32 v78, v70
	v_mov_b32_e32 v79, v70
	v_mov_b32_e32 v80, v70
	v_mov_b32_e32 v81, v70
	v_mov_b32_e32 v94, v70
	v_mov_b32_e32 v95, v70
	v_mov_b32_e32 v96, v70
	v_mov_b32_e32 v97, v70
	v_mov_b32_e32 v90, v70
	v_mov_b32_e32 v91, v70
	v_mov_b32_e32 v92, v70
	v_mov_b32_e32 v93, v70
	v_mov_b32_e32 v82, v70
	v_mov_b32_e32 v83, v70
	v_mov_b32_e32 v84, v70
	v_mov_b32_e32 v85, v70
	v_mov_b32_e32 v86, v70
	v_mov_b32_e32 v87, v70
	v_mov_b32_e32 v88, v70
	v_mov_b32_e32 v89, v70
	v_mov_b32_e32 v10, v70
	v_mov_b32_e32 v11, v70
	v_mov_b32_e32 v12, v70
	v_mov_b32_e32 v13, v70
	v_mov_b32_e32 v14, v70
	v_mov_b32_e32 v15, v70
	v_mov_b32_e32 v16, v70
	v_mov_b32_e32 v17, v70
	v_mov_b32_e32 v6, v70
	v_mov_b32_e32 v7, v70
	v_mov_b32_e32 v8, v70
	v_mov_b32_e32 v9, v70
	v_mov_b32_e32 v2, v70
	v_mov_b32_e32 v3, v70
	v_mov_b32_e32 v4, v70
	v_mov_b32_e32 v5, v70
	v_mov_b32_e32 v26, v70
	v_mov_b32_e32 v27, v70
	v_mov_b32_e32 v28, v70
	v_mov_b32_e32 v29, v70
	v_mov_b32_e32 v30, v70
	v_mov_b32_e32 v31, v70
	v_mov_b32_e32 v32, v70
	v_mov_b32_e32 v33, v70
	v_mov_b32_e32 v22, v70
	v_mov_b32_e32 v23, v70
	v_mov_b32_e32 v24, v70
	v_mov_b32_e32 v25, v70
	v_mov_b32_e32 v18, v70
	v_mov_b32_e32 v19, v70
	v_mov_b32_e32 v20, v70
	v_mov_b32_e32 v21, v70
	v_mov_b32_e32 v34, v70
	v_mov_b32_e32 v35, v70
	v_mov_b32_e32 v36, v70
	v_mov_b32_e32 v37, v70
	v_mov_b32_e32 v38, v70
	v_mov_b32_e32 v39, v70
	v_mov_b32_e32 v40, v70
	v_mov_b32_e32 v41, v70
	v_mov_b32_e32 v46, v70
	v_mov_b32_e32 v47, v70
	v_mov_b32_e32 v48, v70
	v_mov_b32_e32 v49, v70
	v_mov_b32_e32 v50, v70
	v_mov_b32_e32 v51, v70
	v_mov_b32_e32 v52, v70
	v_mov_b32_e32 v53, v70
	v_mov_b32_e32 v42, v70
	v_mov_b32_e32 v43, v70
	v_mov_b32_e32 v44, v70
	v_mov_b32_e32 v45, v70
	v_mov_b32_e32 v54, v70
	v_mov_b32_e32 v55, v70
	v_mov_b32_e32 v56, v70
	v_mov_b32_e32 v57, v70
	v_mov_b32_e32 v58, v70
	v_mov_b32_e32 v59, v70
	v_mov_b32_e32 v60, v70
	v_mov_b32_e32 v61, v70
	v_mov_b32_e32 v62, v70
	v_mov_b32_e32 v63, v70
	v_mov_b32_e32 v64, v70
	v_mov_b32_e32 v65, v70
	v_mov_b32_e32 v98, v70
	v_mov_b32_e32 v99, v70
	v_mov_b32_e32 v100, v70
	v_mov_b32_e32 v101, v70
	v_mov_b32_e32 v102, v70
	v_mov_b32_e32 v103, v70
	v_mov_b32_e32 v104, v70
	v_mov_b32_e32 v105, v70
	v_mov_b32_e32 v106, v70
	v_mov_b32_e32 v107, v70
	v_mov_b32_e32 v108, v70
	v_mov_b32_e32 v109, v70
	v_mov_b32_e32 v118, v70
	v_mov_b32_e32 v119, v70
	v_mov_b32_e32 v120, v70
	v_mov_b32_e32 v121, v70
	v_mov_b32_e32 v110, v70
	v_mov_b32_e32 v111, v70
	v_mov_b32_e32 v112, v70
	v_mov_b32_e32 v113, v70
	v_mov_b32_e32 v114, v70
	v_mov_b32_e32 v115, v70
	v_mov_b32_e32 v116, v70
	v_mov_b32_e32 v117, v70
	v_mov_b32_e32 v122, v70
	v_mov_b32_e32 v123, v70
	v_mov_b32_e32 v124, v70
	v_mov_b32_e32 v125, v70
	v_mov_b32_e32 v126, v70
	v_mov_b32_e32 v127, v70
	v_mov_b32_e32 v128, v70
	v_mov_b32_e32 v129, v70
	s_add_i32 vcc_lo, 0, 0x10000
	v_add_u32_e32 v0, vcc_lo, v254
	ds_read_b128 v[130:133], v0
	ds_read_b128 v[134:137], v0 offset:1024
	ds_read_b128 v[138:141], v0 offset:2048
	ds_read_b128 v[142:145], v0 offset:3072
	s_add_u32 s88, s6, 0x100
	s_addc_u32 s89, s7, 0
	s_cmp_eq_u32 s45, 12
	s_cselect_b32 s93, s17, s89
	s_cselect_b32 s92, s22, s88
	s_cselect_b32 s91, s15, s29
	s_cselect_b32 s90, s23, s28
.LBB0_919:
	v_lshl_add_u64 v[154:155], s[6:7], 0, v[164:165]
	s_add_i32 m0, s43, 0xc000
	ds_read_b128 v[146:149], v253
	ds_read_b128 v[150:153], v253 offset:1024
	ds_read_b128 v[168:171], v253 offset:2048
	ds_read_b128 v[172:175], v253 offset:3072
	ds_read_b128 v[176:179], v253 offset:4096
	ds_read_b128 v[180:183], v253 offset:5120
	ds_read_b128 v[184:187], v253 offset:6144
	ds_read_b128 v[190:193], v253 offset:7168
	global_load_lds_dwordx4 v[154:155], off
	s_add_i32 m0, s43, 0xe000
	v_lshl_add_u64 v[154:155], s[6:7], 0, v[166:167]
	global_load_lds_dwordx4 v[154:155], off
	s_waitcnt lgkmcnt(8)
	s_barrier
	s_waitcnt lgkmcnt(0)
	v_mfma_f32_16x16x32_bf16 v[126:129], v[130:133], v[146:149], v[126:129]
	v_mfma_f32_16x16x32_bf16 v[70:73], v[138:141], v[146:149], v[70:73]
	v_mfma_f32_16x16x32_bf16 v[122:125], v[130:133], v[168:171], v[122:125]
	v_mfma_f32_16x16x32_bf16 v[74:77], v[138:141], v[168:171], v[74:77]
	v_mfma_f32_16x16x32_bf16 v[114:117], v[130:133], v[176:179], v[114:117]
	v_mfma_f32_16x16x32_bf16 v[66:69], v[138:141], v[176:179], v[66:69]
	v_mfma_f32_16x16x32_bf16 v[110:113], v[130:133], v[184:187], v[110:113]
	v_mfma_f32_16x16x32_bf16 v[78:81], v[138:141], v[184:187], v[78:81]
	v_mfma_f32_16x16x32_bf16 v[126:129], v[134:137], v[150:153], v[126:129]
	v_mfma_f32_16x16x32_bf16 v[70:73], v[142:145], v[150:153], v[70:73]
	v_mfma_f32_16x16x32_bf16 v[122:125], v[134:137], v[172:175], v[122:125]
	v_mfma_f32_16x16x32_bf16 v[74:77], v[142:145], v[172:175], v[74:77]
	v_mfma_f32_16x16x32_bf16 v[114:117], v[134:137], v[180:183], v[114:117]
	v_mfma_f32_16x16x32_bf16 v[66:69], v[142:145], v[180:183], v[66:69]
	v_mfma_f32_16x16x32_bf16 v[110:113], v[134:137], v[190:193], v[110:113]
	v_mfma_f32_16x16x32_bf16 v[78:81], v[142:145], v[190:193], v[78:81]
	s_barrier
	s_add_i32 vcc_hi, 0, 0x14000
	s_add_i32 s6, vcc_lo, s39
	v_add_u32_e32 v0, vcc_hi, v254
	v_lshl_add_u64 v[154:155], s[90:91], 0, v[160:161]
	s_mov_b32 m0, s6
	ds_read_b128 v[194:197], v0
	ds_read_b128 v[198:201], v0 offset:1024
	ds_read_b128 v[202:205], v0 offset:2048
	ds_read_b128 v[206:209], v0 offset:3072
	global_load_lds_dwordx4 v[154:155], off
	s_add_i32 m0, s6, 0x2000
	v_lshl_add_u64 v[210:211], s[90:91], 0, v[156:157]
	global_load_lds_dwordx4 v[210:211], off
	s_barrier
	s_waitcnt lgkmcnt(0)
	v_mfma_f32_16x16x32_bf16 v[118:121], v[194:197], v[146:149], v[118:121]
	v_mfma_f32_16x16x32_bf16 v[94:97], v[202:205], v[146:149], v[94:97]
	v_mfma_f32_16x16x32_bf16 v[106:109], v[194:197], v[168:171], v[106:109]
	v_mfma_f32_16x16x32_bf16 v[90:93], v[202:205], v[168:171], v[90:93]
	v_mfma_f32_16x16x32_bf16 v[102:105], v[194:197], v[176:179], v[102:105]
	v_mfma_f32_16x16x32_bf16 v[82:85], v[202:205], v[176:179], v[82:85]
	v_mfma_f32_16x16x32_bf16 v[98:101], v[194:197], v[184:187], v[98:101]
	v_mfma_f32_16x16x32_bf16 v[86:89], v[202:205], v[184:187], v[86:89]
	v_mfma_f32_16x16x32_bf16 v[118:121], v[198:201], v[150:153], v[118:121]
	v_mfma_f32_16x16x32_bf16 v[94:97], v[206:209], v[150:153], v[94:97]
	v_mfma_f32_16x16x32_bf16 v[106:109], v[198:201], v[172:175], v[106:109]
	v_mfma_f32_16x16x32_bf16 v[90:93], v[206:209], v[172:175], v[90:93]
	v_mfma_f32_16x16x32_bf16 v[102:105], v[198:201], v[180:183], v[102:105]
	v_mfma_f32_16x16x32_bf16 v[82:85], v[206:209], v[180:183], v[82:85]
	v_mfma_f32_16x16x32_bf16 v[98:101], v[198:201], v[190:193], v[98:101]
	v_mfma_f32_16x16x32_bf16 v[86:89], v[206:209], v[190:193], v[86:89]
	s_mov_b32 m0, s43
	v_lshl_add_u64 v[212:213], s[92:93], 0, v[162:163]
	s_barrier
	ds_read_b128 v[146:149], v253 offset:16384
	ds_read_b128 v[150:153], v253 offset:17408
	ds_read_b128 v[168:171], v253 offset:18432
	ds_read_b128 v[172:175], v253 offset:19456
	ds_read_b128 v[176:179], v253 offset:20480
	ds_read_b128 v[180:183], v253 offset:21504
	ds_read_b128 v[184:187], v253 offset:22528
	ds_read_b128 v[190:193], v253 offset:23552
	global_load_lds_dwordx4 v[212:213], off
	s_mov_b32 m0, s60
	v_lshl_add_u64 v[214:215], s[92:93], 0, v[158:159]
	global_load_lds_dwordx4 v[214:215], off
	s_waitcnt vmcnt(10)
	s_barrier
	s_waitcnt lgkmcnt(0)
	v_mfma_f32_16x16x32_bf16 v[62:65], v[130:133], v[146:149], v[62:65]
	v_mfma_f32_16x16x32_bf16 v[10:13], v[138:141], v[146:149], v[10:13]
	v_mfma_f32_16x16x32_bf16 v[58:61], v[130:133], v[168:171], v[58:61]
	v_mfma_f32_16x16x32_bf16 v[14:17], v[138:141], v[168:171], v[14:17]
	v_mfma_f32_16x16x32_bf16 v[54:57], v[130:133], v[176:179], v[54:57]
	v_mfma_f32_16x16x32_bf16 v[6:9], v[138:141], v[176:179], v[6:9]
	v_mfma_f32_16x16x32_bf16 v[42:45], v[130:133], v[184:187], v[42:45]
	v_mfma_f32_16x16x32_bf16 v[2:5], v[138:141], v[184:187], v[2:5]
	v_mfma_f32_16x16x32_bf16 v[62:65], v[134:137], v[150:153], v[62:65]
	v_mfma_f32_16x16x32_bf16 v[10:13], v[142:145], v[150:153], v[10:13]
	v_mfma_f32_16x16x32_bf16 v[58:61], v[134:137], v[172:175], v[58:61]
	v_mfma_f32_16x16x32_bf16 v[14:17], v[142:145], v[172:175], v[14:17]
	v_mfma_f32_16x16x32_bf16 v[54:57], v[134:137], v[180:183], v[54:57]
	v_mfma_f32_16x16x32_bf16 v[6:9], v[142:145], v[180:183], v[6:9]
	v_mfma_f32_16x16x32_bf16 v[42:45], v[134:137], v[190:193], v[42:45]
	v_mfma_f32_16x16x32_bf16 v[2:5], v[142:145], v[190:193], v[2:5]
	s_barrier
	s_add_u32 s6, s90, 0x40000
	s_addc_u32 s7, s91, 0
	s_add_i32 vcc_lo, vcc_hi, s39
	s_mov_b32 m0, vcc_lo
	v_lshl_add_u64 v[130:131], s[6:7], 0, v[160:161]
	global_load_lds_dwordx4 v[130:131], off
	s_add_i32 m0, vcc_lo, 0x2000
	v_lshl_add_u64 v[130:131], s[6:7], 0, v[156:157]
	global_load_lds_dwordx4 v[130:131], off
	s_add_i32 vcc_lo, 0, 0x18000
	v_add_u32_e32 v0, vcc_lo, v254
	ds_read_b128 v[130:133], v0
	ds_read_b128 v[134:137], v0 offset:1024
	ds_read_b128 v[138:141], v0 offset:2048
	ds_read_b128 v[142:145], v0 offset:3072
	s_waitcnt vmcnt(6)
	s_barrier
	v_mfma_f32_16x16x32_bf16 v[50:53], v[194:197], v[146:149], v[50:53]
	v_mfma_f32_16x16x32_bf16 v[26:29], v[202:205], v[146:149], v[26:29]
	v_mfma_f32_16x16x32_bf16 v[46:49], v[194:197], v[168:171], v[46:49]
	v_mfma_f32_16x16x32_bf16 v[30:33], v[202:205], v[168:171], v[30:33]
	v_mfma_f32_16x16x32_bf16 v[38:41], v[194:197], v[176:179], v[38:41]
	v_mfma_f32_16x16x32_bf16 v[22:25], v[202:205], v[176:179], v[22:25]
	v_mfma_f32_16x16x32_bf16 v[34:37], v[194:197], v[184:187], v[34:37]
	v_mfma_f32_16x16x32_bf16 v[18:21], v[202:205], v[184:187], v[18:21]
	v_mfma_f32_16x16x32_bf16 v[50:53], v[198:201], v[150:153], v[50:53]
	v_mfma_f32_16x16x32_bf16 v[26:29], v[206:209], v[150:153], v[26:29]
	v_mfma_f32_16x16x32_bf16 v[46:49], v[198:201], v[172:175], v[46:49]
	v_mfma_f32_16x16x32_bf16 v[30:33], v[206:209], v[172:175], v[30:33]
	v_mfma_f32_16x16x32_bf16 v[38:41], v[198:201], v[180:183], v[38:41]
	v_mfma_f32_16x16x32_bf16 v[22:25], v[206:209], v[180:183], v[22:25]
	v_mfma_f32_16x16x32_bf16 v[34:37], v[198:201], v[190:193], v[34:37]
	v_mfma_f32_16x16x32_bf16 v[18:21], v[206:209], v[190:193], v[18:21]
	s_barrier
	s_add_u32 s6, s92, 0x40000
	s_addc_u32 s7, s93, 0
	s_mov_b32 m0, s61
	v_lshl_add_u64 v[194:195], s[6:7], 0, v[162:163]
	ds_read_b128 v[146:149], v253 offset:32768
	ds_read_b128 v[150:153], v253 offset:33792
	ds_read_b128 v[168:171], v253 offset:34816
	ds_read_b128 v[172:175], v253 offset:35840
	ds_read_b128 v[176:179], v253 offset:36864
	ds_read_b128 v[180:183], v253 offset:37888
	ds_read_b128 v[184:187], v253 offset:38912
	ds_read_b128 v[190:193], v253 offset:39936
	global_load_lds_dwordx4 v[194:195], off
	s_mov_b32 m0, s72
	v_lshl_add_u64 v[194:195], s[6:7], 0, v[158:159]
	global_load_lds_dwordx4 v[194:195], off
	s_waitcnt lgkmcnt(8)
	s_barrier
	s_waitcnt lgkmcnt(0)
	v_mfma_f32_16x16x32_bf16 v[126:129], v[130:133], v[146:149], v[126:129]
	v_mfma_f32_16x16x32_bf16 v[70:73], v[138:141], v[146:149], v[70:73]
	v_mfma_f32_16x16x32_bf16 v[122:125], v[130:133], v[168:171], v[122:125]
	v_mfma_f32_16x16x32_bf16 v[74:77], v[138:141], v[168:171], v[74:77]
	v_mfma_f32_16x16x32_bf16 v[114:117], v[130:133], v[176:179], v[114:117]
	v_mfma_f32_16x16x32_bf16 v[66:69], v[138:141], v[176:179], v[66:69]
	v_mfma_f32_16x16x32_bf16 v[110:113], v[130:133], v[184:187], v[110:113]
	v_mfma_f32_16x16x32_bf16 v[78:81], v[138:141], v[184:187], v[78:81]
	v_mfma_f32_16x16x32_bf16 v[126:129], v[134:137], v[150:153], v[126:129]
	v_mfma_f32_16x16x32_bf16 v[70:73], v[142:145], v[150:153], v[70:73]
	v_mfma_f32_16x16x32_bf16 v[122:125], v[134:137], v[172:175], v[122:125]
	v_mfma_f32_16x16x32_bf16 v[74:77], v[142:145], v[172:175], v[74:77]
	v_mfma_f32_16x16x32_bf16 v[114:117], v[134:137], v[180:183], v[114:117]
	v_mfma_f32_16x16x32_bf16 v[66:69], v[142:145], v[180:183], v[66:69]
	v_mfma_f32_16x16x32_bf16 v[110:113], v[134:137], v[190:193], v[110:113]
	v_mfma_f32_16x16x32_bf16 v[78:81], v[142:145], v[190:193], v[78:81]
	s_barrier
	s_add_i32 s92, 0, 0x1c000
	s_add_i32 s6, vcc_lo, s39
	v_add_u32_e32 v0, s92, v254
	v_lshl_add_u64 v[154:155], v[154:155], 0, s[40:41]
	s_mov_b32 m0, s6
	ds_read_b128 v[194:197], v0
	ds_read_b128 v[198:201], v0 offset:1024
	ds_read_b128 v[202:205], v0 offset:2048
	ds_read_b128 v[206:209], v0 offset:3072
	global_load_lds_dwordx4 v[154:155], off
	s_add_i32 m0, s6, 0x2000
	v_lshl_add_u64 v[154:155], v[210:211], 0, s[40:41]
	global_load_lds_dwordx4 v[154:155], off
	s_barrier
	s_waitcnt lgkmcnt(0)
	v_mfma_f32_16x16x32_bf16 v[118:121], v[194:197], v[146:149], v[118:121]
	v_mfma_f32_16x16x32_bf16 v[94:97], v[202:205], v[146:149], v[94:97]
	v_mfma_f32_16x16x32_bf16 v[106:109], v[194:197], v[168:171], v[106:109]
	v_mfma_f32_16x16x32_bf16 v[90:93], v[202:205], v[168:171], v[90:93]
	v_mfma_f32_16x16x32_bf16 v[102:105], v[194:197], v[176:179], v[102:105]
	v_mfma_f32_16x16x32_bf16 v[82:85], v[202:205], v[176:179], v[82:85]
	v_mfma_f32_16x16x32_bf16 v[98:101], v[194:197], v[184:187], v[98:101]
	v_mfma_f32_16x16x32_bf16 v[86:89], v[202:205], v[184:187], v[86:89]
	v_mfma_f32_16x16x32_bf16 v[118:121], v[198:201], v[150:153], v[118:121]
	v_mfma_f32_16x16x32_bf16 v[94:97], v[206:209], v[150:153], v[94:97]
	v_mfma_f32_16x16x32_bf16 v[106:109], v[198:201], v[172:175], v[106:109]
	v_mfma_f32_16x16x32_bf16 v[90:93], v[206:209], v[172:175], v[90:93]
	v_mfma_f32_16x16x32_bf16 v[102:105], v[198:201], v[180:183], v[102:105]
	v_mfma_f32_16x16x32_bf16 v[82:85], v[206:209], v[180:183], v[82:85]
	v_mfma_f32_16x16x32_bf16 v[98:101], v[198:201], v[190:193], v[98:101]
	v_mfma_f32_16x16x32_bf16 v[86:89], v[206:209], v[190:193], v[86:89]
	s_mov_b32 m0, s95
	v_lshl_add_u64 v[154:155], v[212:213], 0, s[40:41]
	s_barrier
	ds_read_b128 v[146:149], v253 offset:49152
	ds_read_b128 v[150:153], v253 offset:50176
	ds_read_b128 v[168:171], v253 offset:51200
	ds_read_b128 v[172:175], v253 offset:52224
	ds_read_b128 v[176:179], v253 offset:53248
	ds_read_b128 v[180:183], v253 offset:54272
	ds_read_b128 v[184:187], v253 offset:55296
	ds_read_b128 v[190:193], v253 offset:56320
	global_load_lds_dwordx4 v[154:155], off
	s_mov_b32 m0, s96
	v_lshl_add_u64 v[154:155], v[214:215], 0, s[40:41]
	global_load_lds_dwordx4 v[154:155], off
	s_waitcnt vmcnt(10)
	s_barrier
	s_waitcnt lgkmcnt(0)
	v_mfma_f32_16x16x32_bf16 v[62:65], v[130:133], v[146:149], v[62:65]
	v_mfma_f32_16x16x32_bf16 v[10:13], v[138:141], v[146:149], v[10:13]
	v_mfma_f32_16x16x32_bf16 v[58:61], v[130:133], v[168:171], v[58:61]
	v_mfma_f32_16x16x32_bf16 v[14:17], v[138:141], v[168:171], v[14:17]
	v_mfma_f32_16x16x32_bf16 v[54:57], v[130:133], v[176:179], v[54:57]
	v_mfma_f32_16x16x32_bf16 v[6:9], v[138:141], v[176:179], v[6:9]
	v_mfma_f32_16x16x32_bf16 v[42:45], v[130:133], v[184:187], v[42:45]
	v_mfma_f32_16x16x32_bf16 v[2:5], v[138:141], v[184:187], v[2:5]
	v_mfma_f32_16x16x32_bf16 v[62:65], v[134:137], v[150:153], v[62:65]
	v_mfma_f32_16x16x32_bf16 v[10:13], v[142:145], v[150:153], v[10:13]
	v_mfma_f32_16x16x32_bf16 v[58:61], v[134:137], v[172:175], v[58:61]
	v_mfma_f32_16x16x32_bf16 v[14:17], v[142:145], v[172:175], v[14:17]
	v_mfma_f32_16x16x32_bf16 v[54:57], v[134:137], v[180:183], v[54:57]
	v_mfma_f32_16x16x32_bf16 v[6:9], v[142:145], v[180:183], v[6:9]
	v_mfma_f32_16x16x32_bf16 v[42:45], v[134:137], v[190:193], v[42:45]
	v_mfma_f32_16x16x32_bf16 v[2:5], v[142:145], v[190:193], v[2:5]
	s_barrier
	s_add_u32 s6, s90, 0x40080
	s_addc_u32 s7, s91, 0
	s_add_i32 s90, s92, s39
	s_mov_b32 m0, s90
	v_lshl_add_u64 v[130:131], s[6:7], 0, v[160:161]
	global_load_lds_dwordx4 v[130:131], off
	s_add_i32 m0, s90, 0x2000
	v_lshl_add_u64 v[130:131], s[6:7], 0, v[156:157]
	global_load_lds_dwordx4 v[130:131], off
	s_add_i32 vcc_lo, 0, 0x10000
	v_add_u32_e32 v0, vcc_lo, v254
	ds_read_b128 v[130:133], v0
	ds_read_b128 v[134:137], v0 offset:1024
	ds_read_b128 v[138:141], v0 offset:2048
	ds_read_b128 v[142:145], v0 offset:3072
	s_waitcnt vmcnt(6)
	s_barrier
	v_mfma_f32_16x16x32_bf16 v[50:53], v[194:197], v[146:149], v[50:53]
	v_mfma_f32_16x16x32_bf16 v[26:29], v[202:205], v[146:149], v[26:29]
	v_mfma_f32_16x16x32_bf16 v[46:49], v[194:197], v[168:171], v[46:49]
	v_mfma_f32_16x16x32_bf16 v[30:33], v[202:205], v[168:171], v[30:33]
	v_mfma_f32_16x16x32_bf16 v[38:41], v[194:197], v[176:179], v[38:41]
	v_mfma_f32_16x16x32_bf16 v[22:25], v[202:205], v[176:179], v[22:25]
	v_mfma_f32_16x16x32_bf16 v[34:37], v[194:197], v[184:187], v[34:37]
	v_mfma_f32_16x16x32_bf16 v[18:21], v[202:205], v[184:187], v[18:21]
	v_mfma_f32_16x16x32_bf16 v[50:53], v[198:201], v[150:153], v[50:53]
	v_mfma_f32_16x16x32_bf16 v[26:29], v[206:209], v[150:153], v[26:29]
	v_mfma_f32_16x16x32_bf16 v[46:49], v[198:201], v[172:175], v[46:49]
	v_mfma_f32_16x16x32_bf16 v[30:33], v[206:209], v[172:175], v[30:33]
	v_mfma_f32_16x16x32_bf16 v[38:41], v[198:201], v[180:183], v[38:41]
	v_mfma_f32_16x16x32_bf16 v[22:25], v[206:209], v[180:183], v[22:25]
	v_mfma_f32_16x16x32_bf16 v[34:37], v[198:201], v[190:193], v[34:37]
	v_mfma_f32_16x16x32_bf16 v[18:21], v[206:209], v[190:193], v[18:21]
	s_add_i32 s45, s45, 2
	s_add_u32 s28, s28, 0x100
	s_addc_u32 s29, s29, 0
	s_mov_b64 s[6:7], s[88:89]
	s_add_u32 s88, s6, 0x100
	s_addc_u32 s89, s7, 0
	s_cmp_eq_u32 s45, 12
	s_cselect_b32 s93, s17, s89
	s_cselect_b32 s92, s22, s88
	s_cselect_b32 s91, s15, s29
	s_cselect_b32 s90, s23, s28
	s_cmp_gt_u32 s45, 13
	s_barrier
	s_cbranch_scc0 .LBB0_919
	s_waitcnt lgkmcnt(0)
	v_mov_b32_e32 v131, v252
	s_lshl_b32 s88, s5, 7
	v_bfe_u32 v130, v131, 4, 2
	v_and_b32_e32 v134, 15, v131
	v_lshlrev_b32_e32 v0, 4, v130
	s_ashr_i32 s89, s88, 31
	s_lshl_b32 s15, s4, 8
	v_or3_b32 v135, v0, s97, v134
	s_lshl_b64 s[4:5], s[88:89], 2
	v_lshrrev_b32_e32 v140, 1, v135
	s_add_u32 s4, s73, s4
	s_addc_u32 s5, s74, s5
	v_lshlrev_b32_e32 v0, 2, v140
	v_and_b32_e32 v144, 1, v131
	v_lshl_add_u64 v[132:133], s[4:5], 0, v[0:1]
	v_cmp_eq_u32_e32 vcc, 1, v144
	v_mov_b32_e32 v0, 0xb00
	s_movk_i32 s4, 0x5000
	v_cndmask_b32_e32 v141, 0, v0, vcc
	v_lshlrev_b32_e32 v0, 2, v141
	v_lshl_add_u64 v[132:133], v[132:133], 0, v[0:1]
	v_add_co_u32_e32 v138, vcc, s4, v132
	s_mov_b32 s4, 0xb000
	s_nop 0
	v_addc_co_u32_e32 v139, vcc, 0, v133, vcc
	global_load_dword v136, v[132:133], off
	global_load_dword v137, v[138:139], off offset:2048
	v_add_co_u32_e32 v132, vcc, s4, v132
	v_add_u32_e32 v0, s88, v141
	s_nop 0
	v_addc_co_u32_e32 v133, vcc, 0, v133, vcc
	global_load_dword v138, v[132:133], off
	v_or_b32_e32 v132, v140, v0
	v_ashrrev_i32_e32 v133, 31, v132
	v_lshl_add_u64 v[132:133], v[132:133], 2, s[12:13]
	global_load_dword v139, v[132:133], off
	v_lshl_add_u32 v0, v135, 4, s78
	v_and_b32_e32 v135, 63, v131
	v_cmp_eq_u32_e32 vcc, 0, v144
	s_waitcnt vmcnt(0)
	ds_write_b128 v0, v[136:139]
	v_or_b32_e32 v0, s97, v135
	v_lshrrev_b32_e32 v0, 1, v0
	v_and_or_b32 v131, v0, 63, s55
	v_add_u32_e32 v132, s15, v131
	v_ashrrev_i32_e32 v133, 31, v132
	v_lshlrev_b64 v[132:133], 6, v[132:133]
	v_lshl_add_u64 v[132:133], s[10:11], 0, v[132:133]
	v_lshlrev_b32_e32 v0, 5, v144
	v_lshl_add_u64 v[132:133], v[132:133], 0, v[0:1]
	global_load_dwordx4 v[136:139], v[132:133], off offset:16
	global_load_dwordx4 v[140:143], v[132:133], off
	s_waitcnt vmcnt(0)
	v_add_f32_e32 v133, v138, v139
	v_add_f32_e32 v0, v140, v141
	v_add_f32_e32 v132, v142, v143
	v_add_f32_e32 v0, v0, v132
	v_add_f32_e32 v132, v136, v137
	v_add_f32_e32 v132, v132, v133
	v_add_f32_e32 v0, v0, v132
	v_lshlrev_b32_e32 v132, 2, v135
	v_xor_b32_e32 v132, 4, v132
	ds_bpermute_b32 v132, v132, v0
	s_and_saveexec_b64 s[4:5], vcc
	s_cbranch_execz .LBB0_922
	s_waitcnt lgkmcnt(0)
	v_add_f32_e32 v0, v0, v132
	v_mov_b32_e32 v132, 0x358637bd
	v_fmamk_f32 v0, v0, 0x3a800000, v132
	s_mov_b32 s6, 0x800000
	v_mul_f32_e32 v132, 0x4b800000, v0
	v_cmp_gt_f32_e32 vcc, s6, v0
	v_lshl_add_u32 v131, v131, 2, 0
	v_add_u32_e32 v131, 0x20000, v131
	v_cndmask_b32_e32 v0, v0, v132, vcc
	v_rsq_f32_e32 v0, v0
	s_nop 0
	v_mul_f32_e32 v132, 0x45800000, v0
	v_cndmask_b32_e32 v0, v0, v132, vcc
	ds_write_b32 v131, v0

.LBB0_1089:
	s_add_u32 s34, s84, 0x100
	v_mov_b32_e32 v2, 0
	s_addc_u32 s78, s85, 0
	s_mov_b32 s79, -2
	s_waitcnt lgkmcnt(0)
	v_mov_b32_e32 v3, v2
	v_mov_b32_e32 v4, v2
	v_mov_b32_e32 v5, v2
	v_mov_b32_e32 v6, v2
	v_mov_b32_e32 v7, v2
	v_mov_b32_e32 v8, v2
	v_mov_b32_e32 v9, v2
	v_mov_b32_e32 v18, v2
	v_mov_b32_e32 v19, v2
	v_mov_b32_e32 v20, v2
	v_mov_b32_e32 v21, v2
	v_mov_b32_e32 v22, v2
	v_mov_b32_e32 v23, v2
	v_mov_b32_e32 v24, v2
	v_mov_b32_e32 v25, v2
	v_mov_b32_e32 v34, v2
	v_mov_b32_e32 v35, v2
	v_mov_b32_e32 v36, v2
	v_mov_b32_e32 v37, v2
	v_mov_b32_e32 v38, v2
	v_mov_b32_e32 v39, v2
	v_mov_b32_e32 v40, v2
	v_mov_b32_e32 v41, v2
	v_mov_b32_e32 v50, v2
	v_mov_b32_e32 v51, v2
	v_mov_b32_e32 v52, v2
	v_mov_b32_e32 v53, v2
	v_mov_b32_e32 v54, v2
	v_mov_b32_e32 v55, v2
	v_mov_b32_e32 v56, v2
	v_mov_b32_e32 v57, v2
	v_mov_b32_e32 v10, v2
	v_mov_b32_e32 v11, v2
	v_mov_b32_e32 v12, v2
	v_mov_b32_e32 v13, v2
	v_mov_b32_e32 v14, v2
	v_mov_b32_e32 v15, v2
	v_mov_b32_e32 v16, v2
	v_mov_b32_e32 v17, v2
	v_mov_b32_e32 v26, v2
	v_mov_b32_e32 v27, v2
	v_mov_b32_e32 v28, v2
	v_mov_b32_e32 v29, v2
	v_mov_b32_e32 v30, v2
	v_mov_b32_e32 v31, v2
	v_mov_b32_e32 v32, v2
	v_mov_b32_e32 v33, v2
	v_mov_b32_e32 v42, v2
	v_mov_b32_e32 v43, v2
	v_mov_b32_e32 v44, v2
	v_mov_b32_e32 v45, v2
	v_mov_b32_e32 v46, v2
	v_mov_b32_e32 v47, v2
	v_mov_b32_e32 v48, v2
	v_mov_b32_e32 v49, v2
	v_mov_b32_e32 v58, v2
	v_mov_b32_e32 v59, v2
	v_mov_b32_e32 v60, v2
	v_mov_b32_e32 v61, v2
	v_mov_b32_e32 v62, v2
	v_mov_b32_e32 v63, v2
	v_mov_b32_e32 v64, v2
	v_mov_b32_e32 v65, v2
	v_mov_b32_e32 v66, v2
	v_mov_b32_e32 v67, v2
	v_mov_b32_e32 v68, v2
	v_mov_b32_e32 v69, v2
	v_mov_b32_e32 v70, v2
	v_mov_b32_e32 v71, v2
	v_mov_b32_e32 v72, v2
	v_mov_b32_e32 v73, v2
	v_mov_b32_e32 v82, v2
	v_mov_b32_e32 v83, v2
	v_mov_b32_e32 v84, v2
	v_mov_b32_e32 v85, v2
	v_mov_b32_e32 v86, v2
	v_mov_b32_e32 v87, v2
	v_mov_b32_e32 v88, v2
	v_mov_b32_e32 v89, v2
	v_mov_b32_e32 v98, v2
	v_mov_b32_e32 v99, v2
	v_mov_b32_e32 v100, v2
	v_mov_b32_e32 v101, v2
	v_mov_b32_e32 v102, v2
	v_mov_b32_e32 v103, v2
	v_mov_b32_e32 v104, v2
	v_mov_b32_e32 v105, v2
	v_mov_b32_e32 v114, v2
	v_mov_b32_e32 v115, v2
	v_mov_b32_e32 v116, v2
	v_mov_b32_e32 v117, v2
	v_mov_b32_e32 v118, v2
	v_mov_b32_e32 v119, v2
	v_mov_b32_e32 v120, v2
	v_mov_b32_e32 v121, v2
	v_mov_b32_e32 v74, v2
	v_mov_b32_e32 v75, v2
	v_mov_b32_e32 v76, v2
	v_mov_b32_e32 v77, v2
	v_mov_b32_e32 v78, v2
	v_mov_b32_e32 v79, v2
	v_mov_b32_e32 v80, v2
	v_mov_b32_e32 v81, v2
	v_mov_b32_e32 v90, v2
	v_mov_b32_e32 v91, v2
	v_mov_b32_e32 v92, v2
	v_mov_b32_e32 v93, v2
	v_mov_b32_e32 v94, v2
	v_mov_b32_e32 v95, v2
	v_mov_b32_e32 v96, v2
	v_mov_b32_e32 v97, v2
	v_mov_b32_e32 v106, v2
	v_mov_b32_e32 v107, v2
	v_mov_b32_e32 v108, v2
	v_mov_b32_e32 v109, v2
	v_mov_b32_e32 v110, v2
	v_mov_b32_e32 v111, v2
	v_mov_b32_e32 v112, v2
	v_mov_b32_e32 v113, v2
	v_mov_b32_e32 v122, v2
	v_mov_b32_e32 v123, v2
	v_mov_b32_e32 v124, v2
	v_mov_b32_e32 v125, v2
	v_mov_b32_e32 v126, v2
	v_mov_b32_e32 v127, v2
	v_mov_b32_e32 v128, v2
	v_mov_b32_e32 v129, v2
	s_add_i32 s90, 0, 0x10000
	v_add_u32_e32 v142, s90, v212
	ds_read_b128 v[130:133], v142
	ds_read_b128 v[134:137], v142 offset:1024
	ds_read_b128 v[138:141], v142 offset:2048
	ds_read_b128 v[142:145], v142 offset:3072
	s_add_u32 s84, s16, 0x100
	s_addc_u32 s85, s17, 0
	s_cmp_eq_u32 s79, 40
	s_cselect_b32 s89, s5, s85
	s_cselect_b32 s88, s4, s84
	s_cselect_b32 s87, s7, s78
	s_cselect_b32 s86, s6, s34
.LBB0_1090:
	v_lshl_add_u64 v[178:179], s[16:17], 0, v[196:197]
	s_add_i32 m0, s39, 0xc000
	ds_read_b128 v[146:149], v213
	ds_read_b128 v[150:153], v213 offset:1024
	ds_read_b128 v[154:157], v213 offset:2048
	ds_read_b128 v[158:161], v213 offset:3072
	ds_read_b128 v[162:165], v213 offset:4096
	ds_read_b128 v[166:169], v213 offset:5120
	ds_read_b128 v[170:173], v213 offset:6144
	ds_read_b128 v[174:177], v213 offset:7168
	global_load_lds_dwordx4 v[178:179], off
	s_add_i32 m0, s39, 0xe000
	v_lshl_add_u64 v[178:179], s[16:17], 0, v[198:199]
	global_load_lds_dwordx4 v[178:179], off
	s_waitcnt lgkmcnt(8)
	s_barrier
	s_waitcnt lgkmcnt(0)
	v_mfma_f32_16x16x32_bf16 v[126:129], v[130:133], v[146:149], v[126:129]
	v_mfma_f32_16x16x32_bf16 v[122:125], v[138:141], v[146:149], v[122:125]
	v_mfma_f32_16x16x32_bf16 v[110:113], v[130:133], v[154:157], v[110:113]
	v_mfma_f32_16x16x32_bf16 v[106:109], v[138:141], v[154:157], v[106:109]
	v_mfma_f32_16x16x32_bf16 v[94:97], v[130:133], v[162:165], v[94:97]
	v_mfma_f32_16x16x32_bf16 v[90:93], v[138:141], v[162:165], v[90:93]
	v_mfma_f32_16x16x32_bf16 v[78:81], v[130:133], v[170:173], v[78:81]
	v_mfma_f32_16x16x32_bf16 v[74:77], v[138:141], v[170:173], v[74:77]
	v_mfma_f32_16x16x32_bf16 v[126:129], v[134:137], v[150:153], v[126:129]
	v_mfma_f32_16x16x32_bf16 v[122:125], v[142:145], v[150:153], v[122:125]
	v_mfma_f32_16x16x32_bf16 v[110:113], v[134:137], v[158:161], v[110:113]
	v_mfma_f32_16x16x32_bf16 v[106:109], v[142:145], v[158:161], v[106:109]
	v_mfma_f32_16x16x32_bf16 v[94:97], v[134:137], v[166:169], v[94:97]
	v_mfma_f32_16x16x32_bf16 v[90:93], v[142:145], v[166:169], v[90:93]
	v_mfma_f32_16x16x32_bf16 v[78:81], v[134:137], v[174:177], v[78:81]
	v_mfma_f32_16x16x32_bf16 v[74:77], v[142:145], v[174:177], v[74:77]
	s_barrier
	s_add_i32 s91, 0, 0x14000
	v_add_u32_e32 v186, s91, v212
	s_add_i32 s16, s90, s38
	ds_read_b128 v[178:181], v186
	ds_read_b128 v[182:185], v186 offset:1024
	ds_read_b128 v[200:203], v186 offset:2048
	ds_read_b128 v[204:207], v186 offset:3072
	v_lshl_add_u64 v[186:187], s[86:87], 0, v[0:1]
	s_mov_b32 m0, s16
	v_lshl_add_u64 v[208:209], s[86:87], 0, v[194:195]
	global_load_lds_dwordx4 v[186:187], off
	s_add_i32 m0, s16, 0x2000
	s_nop 0
	global_load_lds_dwordx4 v[208:209], off
	s_barrier
	s_waitcnt lgkmcnt(0)
	v_mfma_f32_16x16x32_bf16 v[118:121], v[178:181], v[146:149], v[118:121]
	v_mfma_f32_16x16x32_bf16 v[114:117], v[200:203], v[146:149], v[114:117]
	v_mfma_f32_16x16x32_bf16 v[102:105], v[178:181], v[154:157], v[102:105]
	v_mfma_f32_16x16x32_bf16 v[98:101], v[200:203], v[154:157], v[98:101]
	v_mfma_f32_16x16x32_bf16 v[86:89], v[178:181], v[162:165], v[86:89]
	v_mfma_f32_16x16x32_bf16 v[82:85], v[200:203], v[162:165], v[82:85]
	v_mfma_f32_16x16x32_bf16 v[70:73], v[178:181], v[170:173], v[70:73]
	v_mfma_f32_16x16x32_bf16 v[66:69], v[200:203], v[170:173], v[66:69]
	v_mfma_f32_16x16x32_bf16 v[118:121], v[182:185], v[150:153], v[118:121]
	v_mfma_f32_16x16x32_bf16 v[114:117], v[204:207], v[150:153], v[114:117]
	v_mfma_f32_16x16x32_bf16 v[102:105], v[182:185], v[158:161], v[102:105]
	v_mfma_f32_16x16x32_bf16 v[98:101], v[204:207], v[158:161], v[98:101]
	v_mfma_f32_16x16x32_bf16 v[86:89], v[182:185], v[166:169], v[86:89]
	v_mfma_f32_16x16x32_bf16 v[82:85], v[204:207], v[166:169], v[82:85]
	v_mfma_f32_16x16x32_bf16 v[70:73], v[182:185], v[174:177], v[70:73]
	v_mfma_f32_16x16x32_bf16 v[66:69], v[204:207], v[174:177], v[66:69]
	s_mov_b32 m0, s39
	v_lshl_add_u64 v[210:211], s[88:89], 0, v[190:191]
	s_barrier
	ds_read_b128 v[146:149], v213 offset:16384
	ds_read_b128 v[150:153], v213 offset:17408
	ds_read_b128 v[154:157], v213 offset:18432
	ds_read_b128 v[158:161], v213 offset:19456
	ds_read_b128 v[162:165], v213 offset:20480
	ds_read_b128 v[166:169], v213 offset:21504
	ds_read_b128 v[170:173], v213 offset:22528
	ds_read_b128 v[174:177], v213 offset:23552
	global_load_lds_dwordx4 v[210:211], off
	s_mov_b32 m0, s42
	v_lshl_add_u64 v[214:215], s[88:89], 0, v[192:193]
	global_load_lds_dwordx4 v[214:215], off
	s_waitcnt vmcnt(10)
	s_barrier
	s_waitcnt lgkmcnt(0)
	v_mfma_f32_16x16x32_bf16 v[62:65], v[130:133], v[146:149], v[62:65]
	v_mfma_f32_16x16x32_bf16 v[58:61], v[138:141], v[146:149], v[58:61]
	v_mfma_f32_16x16x32_bf16 v[46:49], v[130:133], v[154:157], v[46:49]
	v_mfma_f32_16x16x32_bf16 v[42:45], v[138:141], v[154:157], v[42:45]
	v_mfma_f32_16x16x32_bf16 v[30:33], v[130:133], v[162:165], v[30:33]
	v_mfma_f32_16x16x32_bf16 v[26:29], v[138:141], v[162:165], v[26:29]
	v_mfma_f32_16x16x32_bf16 v[14:17], v[130:133], v[170:173], v[14:17]
	v_mfma_f32_16x16x32_bf16 v[10:13], v[138:141], v[170:173], v[10:13]
	v_mfma_f32_16x16x32_bf16 v[62:65], v[134:137], v[150:153], v[62:65]
	v_mfma_f32_16x16x32_bf16 v[58:61], v[142:145], v[150:153], v[58:61]
	v_mfma_f32_16x16x32_bf16 v[46:49], v[134:137], v[158:161], v[46:49]
	v_mfma_f32_16x16x32_bf16 v[42:45], v[142:145], v[158:161], v[42:45]
	v_mfma_f32_16x16x32_bf16 v[30:33], v[134:137], v[166:169], v[30:33]
	v_mfma_f32_16x16x32_bf16 v[26:29], v[142:145], v[166:169], v[26:29]
	v_mfma_f32_16x16x32_bf16 v[14:17], v[134:137], v[174:177], v[14:17]
	v_mfma_f32_16x16x32_bf16 v[10:13], v[142:145], v[174:177], v[10:13]
	s_barrier
	s_add_u32 s16, s86, 0xb0000
	s_addc_u32 s17, s87, 0
	s_add_i32 s90, s91, s38
	s_mov_b32 m0, s90
	v_lshl_add_u64 v[130:131], s[16:17], 0, v[0:1]
	global_load_lds_dwordx4 v[130:131], off
	s_add_i32 m0, s90, 0x2000
	v_lshl_add_u64 v[130:131], s[16:17], 0, v[194:195]
	global_load_lds_dwordx4 v[130:131], off
	s_add_i32 s90, 0, 0x18000
	v_add_u32_e32 v142, s90, v212
	ds_read_b128 v[130:133], v142
	ds_read_b128 v[134:137], v142 offset:1024
	ds_read_b128 v[138:141], v142 offset:2048
	ds_read_b128 v[142:145], v142 offset:3072
	s_waitcnt vmcnt(6)
	s_barrier
	v_mfma_f32_16x16x32_bf16 v[54:57], v[178:181], v[146:149], v[54:57]
	v_mfma_f32_16x16x32_bf16 v[50:53], v[200:203], v[146:149], v[50:53]
	v_mfma_f32_16x16x32_bf16 v[38:41], v[178:181], v[154:157], v[38:41]
	v_mfma_f32_16x16x32_bf16 v[34:37], v[200:203], v[154:157], v[34:37]
	v_mfma_f32_16x16x32_bf16 v[22:25], v[178:181], v[162:165], v[22:25]
	v_mfma_f32_16x16x32_bf16 v[18:21], v[200:203], v[162:165], v[18:21]
	v_mfma_f32_16x16x32_bf16 v[6:9], v[178:181], v[170:173], v[6:9]
	v_mfma_f32_16x16x32_bf16 v[2:5], v[200:203], v[170:173], v[2:5]
	v_mfma_f32_16x16x32_bf16 v[54:57], v[182:185], v[150:153], v[54:57]
	v_mfma_f32_16x16x32_bf16 v[50:53], v[204:207], v[150:153], v[50:53]
	v_mfma_f32_16x16x32_bf16 v[38:41], v[182:185], v[158:161], v[38:41]
	v_mfma_f32_16x16x32_bf16 v[34:37], v[204:207], v[158:161], v[34:37]
	v_mfma_f32_16x16x32_bf16 v[22:25], v[182:185], v[166:169], v[22:25]
	v_mfma_f32_16x16x32_bf16 v[18:21], v[204:207], v[166:169], v[18:21]
	v_mfma_f32_16x16x32_bf16 v[6:9], v[182:185], v[174:177], v[6:9]
	v_mfma_f32_16x16x32_bf16 v[2:5], v[204:207], v[174:177], v[2:5]
	s_barrier
	s_add_u32 s16, s88, 0xb0000
	s_addc_u32 s17, s89, 0
	s_mov_b32 m0, s43
	v_lshl_add_u64 v[178:179], s[16:17], 0, v[190:191]
	ds_read_b128 v[146:149], v213 offset:32768
	ds_read_b128 v[150:153], v213 offset:33792
	ds_read_b128 v[154:157], v213 offset:34816
	ds_read_b128 v[158:161], v213 offset:35840
	ds_read_b128 v[162:165], v213 offset:36864
	ds_read_b128 v[166:169], v213 offset:37888
	ds_read_b128 v[170:173], v213 offset:38912
	ds_read_b128 v[174:177], v213 offset:39936
	global_load_lds_dwordx4 v[178:179], off
	s_mov_b32 m0, s44
	v_lshl_add_u64 v[178:179], s[16:17], 0, v[192:193]
	global_load_lds_dwordx4 v[178:179], off
	s_waitcnt lgkmcnt(8)
	s_barrier
	s_waitcnt lgkmcnt(0)
	v_mfma_f32_16x16x32_bf16 v[126:129], v[130:133], v[146:149], v[126:129]
	v_mfma_f32_16x16x32_bf16 v[122:125], v[138:141], v[146:149], v[122:125]
	v_mfma_f32_16x16x32_bf16 v[110:113], v[130:133], v[154:157], v[110:113]
	v_mfma_f32_16x16x32_bf16 v[106:109], v[138:141], v[154:157], v[106:109]
	v_mfma_f32_16x16x32_bf16 v[94:97], v[130:133], v[162:165], v[94:97]
	v_mfma_f32_16x16x32_bf16 v[90:93], v[138:141], v[162:165], v[90:93]
	v_mfma_f32_16x16x32_bf16 v[78:81], v[130:133], v[170:173], v[78:81]
	v_mfma_f32_16x16x32_bf16 v[74:77], v[138:141], v[170:173], v[74:77]
	v_mfma_f32_16x16x32_bf16 v[126:129], v[134:137], v[150:153], v[126:129]
	v_mfma_f32_16x16x32_bf16 v[122:125], v[142:145], v[150:153], v[122:125]
	v_mfma_f32_16x16x32_bf16 v[110:113], v[134:137], v[158:161], v[110:113]
	v_mfma_f32_16x16x32_bf16 v[106:109], v[142:145], v[158:161], v[106:109]
	v_mfma_f32_16x16x32_bf16 v[94:97], v[134:137], v[166:169], v[94:97]
	v_mfma_f32_16x16x32_bf16 v[90:93], v[142:145], v[166:169], v[90:93]
	v_mfma_f32_16x16x32_bf16 v[78:81], v[134:137], v[174:177], v[78:81]
	v_mfma_f32_16x16x32_bf16 v[74:77], v[142:145], v[174:177], v[74:77]
	s_barrier
	s_add_i32 s88, 0, 0x1c000
	s_add_i32 s16, s90, s38
	v_add_u32_e32 v204, s88, v212
	v_lshl_add_u64 v[186:187], v[186:187], 0, s[40:41]
	s_mov_b32 m0, s16
	ds_read_b128 v[178:181], v204
	ds_read_b128 v[182:185], v204 offset:1024
	ds_read_b128 v[200:203], v204 offset:2048
	ds_read_b128 v[204:207], v204 offset:3072
	global_load_lds_dwordx4 v[186:187], off
	s_add_i32 m0, s16, 0x2000
	v_lshl_add_u64 v[186:187], v[208:209], 0, s[40:41]
	global_load_lds_dwordx4 v[186:187], off
	s_barrier
	s_waitcnt lgkmcnt(0)
	v_mfma_f32_16x16x32_bf16 v[118:121], v[178:181], v[146:149], v[118:121]
	v_mfma_f32_16x16x32_bf16 v[114:117], v[200:203], v[146:149], v[114:117]
	v_mfma_f32_16x16x32_bf16 v[102:105], v[178:181], v[154:157], v[102:105]
	v_mfma_f32_16x16x32_bf16 v[98:101], v[200:203], v[154:157], v[98:101]
	v_mfma_f32_16x16x32_bf16 v[86:89], v[178:181], v[162:165], v[86:89]
	v_mfma_f32_16x16x32_bf16 v[82:85], v[200:203], v[162:165], v[82:85]
	v_mfma_f32_16x16x32_bf16 v[70:73], v[178:181], v[170:173], v[70:73]
	v_mfma_f32_16x16x32_bf16 v[66:69], v[200:203], v[170:173], v[66:69]
	v_mfma_f32_16x16x32_bf16 v[118:121], v[182:185], v[150:153], v[118:121]
	v_mfma_f32_16x16x32_bf16 v[114:117], v[204:207], v[150:153], v[114:117]
	v_mfma_f32_16x16x32_bf16 v[102:105], v[182:185], v[158:161], v[102:105]
	v_mfma_f32_16x16x32_bf16 v[98:101], v[204:207], v[158:161], v[98:101]
	v_mfma_f32_16x16x32_bf16 v[86:89], v[182:185], v[166:169], v[86:89]
	v_mfma_f32_16x16x32_bf16 v[82:85], v[204:207], v[166:169], v[82:85]
	v_mfma_f32_16x16x32_bf16 v[70:73], v[182:185], v[174:177], v[70:73]
	v_mfma_f32_16x16x32_bf16 v[66:69], v[204:207], v[174:177], v[66:69]
	s_mov_b32 m0, s60
	v_lshl_add_u64 v[186:187], v[210:211], 0, s[40:41]
	s_barrier
	ds_read_b128 v[146:149], v213 offset:49152
	ds_read_b128 v[150:153], v213 offset:50176
	ds_read_b128 v[154:157], v213 offset:51200
	ds_read_b128 v[158:161], v213 offset:52224
	ds_read_b128 v[162:165], v213 offset:53248
	ds_read_b128 v[166:169], v213 offset:54272
	ds_read_b128 v[170:173], v213 offset:55296
	ds_read_b128 v[174:177], v213 offset:56320
	global_load_lds_dwordx4 v[186:187], off
	s_mov_b32 m0, s61
	v_lshl_add_u64 v[186:187], v[214:215], 0, s[40:41]
	global_load_lds_dwordx4 v[186:187], off
	s_waitcnt vmcnt(10)
	s_barrier
	s_waitcnt lgkmcnt(0)
	v_mfma_f32_16x16x32_bf16 v[62:65], v[130:133], v[146:149], v[62:65]
	v_mfma_f32_16x16x32_bf16 v[58:61], v[138:141], v[146:149], v[58:61]
	v_mfma_f32_16x16x32_bf16 v[46:49], v[130:133], v[154:157], v[46:49]
	v_mfma_f32_16x16x32_bf16 v[42:45], v[138:141], v[154:157], v[42:45]
	v_mfma_f32_16x16x32_bf16 v[30:33], v[130:133], v[162:165], v[30:33]
	v_mfma_f32_16x16x32_bf16 v[26:29], v[138:141], v[162:165], v[26:29]
	v_mfma_f32_16x16x32_bf16 v[14:17], v[130:133], v[170:173], v[14:17]
	v_mfma_f32_16x16x32_bf16 v[10:13], v[138:141], v[170:173], v[10:13]
	v_mfma_f32_16x16x32_bf16 v[62:65], v[134:137], v[150:153], v[62:65]
	v_mfma_f32_16x16x32_bf16 v[58:61], v[142:145], v[150:153], v[58:61]
	v_mfma_f32_16x16x32_bf16 v[46:49], v[134:137], v[158:161], v[46:49]
	v_mfma_f32_16x16x32_bf16 v[42:45], v[142:145], v[158:161], v[42:45]
	v_mfma_f32_16x16x32_bf16 v[30:33], v[134:137], v[166:169], v[30:33]
	v_mfma_f32_16x16x32_bf16 v[26:29], v[142:145], v[166:169], v[26:29]
	v_mfma_f32_16x16x32_bf16 v[14:17], v[134:137], v[174:177], v[14:17]
	v_mfma_f32_16x16x32_bf16 v[10:13], v[142:145], v[174:177], v[10:13]
	s_barrier
	s_add_u32 s16, s86, 0xb0080
	s_addc_u32 s17, s87, 0
	s_add_i32 s86, s88, s38
	s_mov_b32 m0, s86
	v_lshl_add_u64 v[130:131], s[16:17], 0, v[0:1]
	global_load_lds_dwordx4 v[130:131], off
	s_add_i32 m0, s86, 0x2000
	v_lshl_add_u64 v[130:131], s[16:17], 0, v[194:195]
	global_load_lds_dwordx4 v[130:131], off
	s_add_i32 s90, 0, 0x10000
	v_add_u32_e32 v142, s90, v212
	ds_read_b128 v[130:133], v142
	ds_read_b128 v[134:137], v142 offset:1024
	ds_read_b128 v[138:141], v142 offset:2048
	ds_read_b128 v[142:145], v142 offset:3072
	s_waitcnt vmcnt(6)
	s_barrier
	v_mfma_f32_16x16x32_bf16 v[54:57], v[178:181], v[146:149], v[54:57]
	v_mfma_f32_16x16x32_bf16 v[50:53], v[200:203], v[146:149], v[50:53]
	v_mfma_f32_16x16x32_bf16 v[38:41], v[178:181], v[154:157], v[38:41]
	v_mfma_f32_16x16x32_bf16 v[34:37], v[200:203], v[154:157], v[34:37]
	v_mfma_f32_16x16x32_bf16 v[22:25], v[178:181], v[162:165], v[22:25]
	v_mfma_f32_16x16x32_bf16 v[18:21], v[200:203], v[162:165], v[18:21]
	v_mfma_f32_16x16x32_bf16 v[6:9], v[178:181], v[170:173], v[6:9]
	v_mfma_f32_16x16x32_bf16 v[2:5], v[200:203], v[170:173], v[2:5]
	v_mfma_f32_16x16x32_bf16 v[54:57], v[182:185], v[150:153], v[54:57]
	v_mfma_f32_16x16x32_bf16 v[50:53], v[204:207], v[150:153], v[50:53]
	v_mfma_f32_16x16x32_bf16 v[38:41], v[182:185], v[158:161], v[38:41]
	v_mfma_f32_16x16x32_bf16 v[34:37], v[204:207], v[158:161], v[34:37]
	v_mfma_f32_16x16x32_bf16 v[22:25], v[182:185], v[166:169], v[22:25]
	v_mfma_f32_16x16x32_bf16 v[18:21], v[204:207], v[166:169], v[18:21]
	v_mfma_f32_16x16x32_bf16 v[6:9], v[182:185], v[174:177], v[6:9]
	v_mfma_f32_16x16x32_bf16 v[2:5], v[204:207], v[174:177], v[2:5]
	s_add_i32 s79, s79, 2
	s_add_u32 s34, s34, 0x100
	s_addc_u32 s78, s78, 0
	s_mov_b64 s[16:17], s[84:85]
	s_add_u32 s84, s16, 0x100
	s_addc_u32 s85, s17, 0
	s_cmp_eq_u32 s79, 40
	s_cselect_b32 s89, s5, s85
	s_cselect_b32 s88, s4, s84
	s_cselect_b32 s87, s7, s78
	s_cselect_b32 s86, s6, s34
	s_cmp_gt_u32 s79, 41
	s_barrier
	s_cbranch_scc0 .LBB0_1090
	s_waitcnt lgkmcnt(0)
	s_lshl_b32 s16, s23, 8
	v_mov_b32_e32 v186, v252
	s_add_i32 s16, s16, s47
	s_nop 0
	v_and_or_b32 v202, v186, 15, s16
	s_lshl_b32 s16, s22, 8
	s_or_b32 s16, s16, s55
	v_lshrrev_b32_e32 v130, 1, v186
	v_and_or_b32 v200, v130, 24, s16
	v_ashrrev_i32_e32 v201, 31, v200
	v_ashrrev_i32_e32 v203, 31, v202
	v_lshl_add_u64 v[204:205], v[200:201], 2, s[12:13]
	v_lshlrev_b64 v[130:131], 12, v[202:203]
	v_lshl_add_u64 v[130:131], v[204:205], 0, v[130:131]
	global_load_dwordx4 v[216:219], v[130:131], off offset:16
	global_load_dwordx4 v[220:223], v[130:131], off
	global_load_dwordx4 v[178:181], v[130:131], off offset:528
	global_load_dwordx4 v[182:185], v[130:131], off offset:512
	v_or_b32_e32 v210, 16, v202
	v_ashrrev_i32_e32 v211, 31, v210
	v_lshlrev_b64 v[130:131], 12, v[210:211]
	v_or_b32_e32 v208, 32, v202
	v_lshl_add_u64 v[130:131], v[204:205], 0, v[130:131]
	v_ashrrev_i32_e32 v209, 31, v208
	global_load_dwordx4 v[170:173], v[130:131], off offset:16
	global_load_dwordx4 v[174:177], v[130:131], off
	global_load_dwordx4 v[162:165], v[130:131], off offset:528
	global_load_dwordx4 v[166:169], v[130:131], off offset:512
	v_lshlrev_b64 v[130:131], 12, v[208:209]
	v_or_b32_e32 v206, 48, v202
	v_lshl_add_u64 v[130:131], v[204:205], 0, v[130:131]
	v_ashrrev_i32_e32 v207, 31, v206
	global_load_dwordx4 v[154:157], v[130:131], off offset:16
	global_load_dwordx4 v[158:161], v[130:131], off
	global_load_dwordx4 v[138:141], v[130:131], off offset:528
	global_load_dwordx4 v[142:145], v[130:131], off offset:512
	v_lshlrev_b64 v[130:131], 12, v[206:207]
	v_lshl_add_u64 v[134:135], v[204:205], 0, v[130:131]
	global_load_dwordx4 v[146:149], v[134:135], off offset:16
	global_load_dwordx4 v[150:153], v[134:135], off
	global_load_dwordx4 v[130:133], v[134:135], off offset:528
	s_nop 0
	global_load_dwordx4 v[134:137], v[134:135], off offset:512
	v_and_b32_e32 v186, 63, v186
	v_lshlrev_b32_e32 v187, 2, v186
	v_xor_b32_e32 v215, 64, v187
	v_xor_b32_e32 v214, 0x80, v187
	v_cmp_gt_u32_e32 vcc, 16, v186
	v_lshlrev_b64 v[186:187], 10, v[202:203]
	v_lshl_add_u64 v[186:187], v[186:187], 0, v[200:201]
	s_lshl_b32 s16, s22, 2
	s_ashr_i32 s17, s16, 31
	s_waitcnt vmcnt(0)
	v_pk_add_f32 v[124:125], v[124:125], v[218:219]
	v_pk_add_f32 v[128:129], v[128:129], v[222:223]
	v_pk_add_f32 v[126:127], v[126:127], v[220:221]
	v_pk_mul_f32 v[218:219], v[128:129], v[128:129]
	v_pk_mul_f32 v[220:221], v[126:127], v[126:127]
	v_pk_add_f32 v[122:123], v[122:123], v[216:217]
	v_lshl_add_u64 v[216:217], v[186:187], 2, s[14:15]
	v_add_f32_e32 v220, v220, v221
	v_add_f32_e32 v218, v218, v219
	global_store_dwordx4 v[216:217], v[126:129], off
	global_store_dwordx4 v[216:217], v[122:125], off offset:16
	v_add_f32_e32 v222, v220, v218
	v_pk_mul_f32 v[220:221], v[122:123], v[122:123]
	v_cvt_pk_bf16_f32 v126, v126, v127
	v_cvt_pk_bf16_f32 v127, v128, v129
	v_cvt_pk_bf16_f32 v128, v122, v123
	v_cvt_pk_bf16_f32 v129, v124, v125
	v_lshl_add_u64 v[122:123], v[186:187], 1, s[80:81]
	v_pk_add_f32 v[120:121], v[120:121], v[184:185]
	v_pk_add_f32 v[118:119], v[118:119], v[182:183]
	v_pk_mul_f32 v[218:219], v[124:125], v[124:125]
	global_store_dwordx4 v[122:123], v[126:129], off
	v_pk_mul_f32 v[124:125], v[120:121], v[120:121]
	v_pk_add_f32 v[116:117], v[116:117], v[180:181]
	v_pk_mul_f32 v[126:127], v[118:119], v[118:119]
	v_pk_add_f32 v[114:115], v[114:115], v[178:179]
	v_add_f32_e32 v126, v126, v127
	v_add_f32_e32 v124, v124, v125
	v_add_f32_e32 v128, v126, v124
	v_pk_mul_f32 v[124:125], v[116:117], v[116:117]
	v_pk_mul_f32 v[126:127], v[114:115], v[114:115]
	v_add_f32_e32 v220, v220, v221
	v_add_f32_e32 v218, v218, v219
	v_add_f32_e32 v126, v126, v127
	v_add_f32_e32 v124, v124, v125
	v_add_f32_e32 v218, v220, v218
	v_add_f32_e32 v124, v126, v124
	v_add_f32_e32 v218, v222, v218
	v_add_f32_e32 v124, v128, v124
	v_add_f32_e32 v124, v218, v124
	global_store_dwordx4 v[216:217], v[118:121], off offset:512
	global_store_dwordx4 v[216:217], v[114:117], off offset:528
	s_nop 0
	v_cvt_pk_bf16_f32 v118, v118, v119
	v_cvt_pk_bf16_f32 v119, v120, v121
	v_cvt_pk_bf16_f32 v120, v114, v115
	ds_bpermute_b32 v114, v215, v124
	v_cvt_pk_bf16_f32 v121, v116, v117
	global_store_dwordx4 v[122:123], v[118:121], off offset:256
	s_waitcnt lgkmcnt(0)
	v_add_f32_e32 v114, v124, v114
	ds_bpermute_b32 v115, v214, v114
	s_and_saveexec_b64 s[22:23], vcc
	s_cbranch_execz .LBB0_1093
	v_lshlrev_b64 v[116:117], 6, v[202:203]
	v_lshl_add_u64 v[116:117], s[82:83], 0, v[116:117]
	v_lshl_add_u64 v[116:117], s[16:17], 2, v[116:117]
	s_lshl_b32 s34, s45, 2
	v_lshl_add_u64 v[116:117], v[116:117], 0, s[34:35]
	s_waitcnt lgkmcnt(0)
	v_add_f32_e32 v114, v114, v115
	global_store_dword v[116:117], v114, off

.LBB0_1208:
	s_ashr_i32 s13, s12, 31
	v_cmp_lt_i64_e32 vcc, s[14:15], v[230:231]
	s_lshl_b64 s[14:15], s[12:13], 19
	s_add_u32 s14, s80, s14
	s_addc_u32 s15, s81, s15
	s_and_b64 s[16:17], vcc, exec
	s_cselect_b32 s13, s15, s89
	s_cselect_b32 s22, s14, s88
	s_ashr_i32 s7, s6, 31
	s_lshl_b64 s[16:17], s[6:7], 19
	s_add_u32 s16, s36, s16
	s_addc_u32 s17, s37, s17
	s_and_b64 s[92:93], vcc, exec
	s_cselect_b32 s7, s17, s91
	s_cselect_b32 s23, s16, s90
	s_add_u32 s88, s88, 0x40080
	s_addc_u32 s89, s89, 0
	s_add_u32 s34, s90, 0x100
	v_mov_b32_e32 v2, 0
	s_addc_u32 s79, s91, 0
	s_mov_b32 s85, -2
	v_mov_b32_e32 v3, v2
	v_mov_b32_e32 v4, v2
	v_mov_b32_e32 v5, v2
	v_mov_b32_e32 v6, v2
	v_mov_b32_e32 v7, v2
	v_mov_b32_e32 v8, v2
	v_mov_b32_e32 v9, v2
	v_mov_b32_e32 v18, v2
	v_mov_b32_e32 v19, v2
	v_mov_b32_e32 v20, v2
	v_mov_b32_e32 v21, v2
	v_mov_b32_e32 v22, v2
	v_mov_b32_e32 v23, v2
	v_mov_b32_e32 v24, v2
	v_mov_b32_e32 v25, v2
	v_mov_b32_e32 v34, v2
	v_mov_b32_e32 v35, v2
	v_mov_b32_e32 v36, v2
	v_mov_b32_e32 v37, v2
	v_mov_b32_e32 v38, v2
	v_mov_b32_e32 v39, v2
	v_mov_b32_e32 v40, v2
	v_mov_b32_e32 v41, v2
	v_mov_b32_e32 v50, v2
	v_mov_b32_e32 v51, v2
	v_mov_b32_e32 v52, v2
	v_mov_b32_e32 v53, v2
	v_mov_b32_e32 v54, v2
	v_mov_b32_e32 v55, v2
	v_mov_b32_e32 v56, v2
	v_mov_b32_e32 v57, v2
	v_mov_b32_e32 v10, v2
	v_mov_b32_e32 v11, v2
	v_mov_b32_e32 v12, v2
	v_mov_b32_e32 v13, v2
	v_mov_b32_e32 v14, v2
	v_mov_b32_e32 v15, v2
	v_mov_b32_e32 v16, v2
	v_mov_b32_e32 v17, v2
	v_mov_b32_e32 v26, v2
	v_mov_b32_e32 v27, v2
	v_mov_b32_e32 v28, v2
	v_mov_b32_e32 v29, v2
	v_mov_b32_e32 v30, v2
	v_mov_b32_e32 v31, v2
	v_mov_b32_e32 v32, v2
	v_mov_b32_e32 v33, v2
	v_mov_b32_e32 v42, v2
	v_mov_b32_e32 v43, v2
	v_mov_b32_e32 v44, v2
	v_mov_b32_e32 v45, v2
	v_mov_b32_e32 v46, v2
	v_mov_b32_e32 v47, v2
	v_mov_b32_e32 v48, v2
	v_mov_b32_e32 v49, v2
	v_mov_b32_e32 v58, v2
	v_mov_b32_e32 v59, v2
	v_mov_b32_e32 v60, v2
	v_mov_b32_e32 v61, v2
	v_mov_b32_e32 v62, v2
	v_mov_b32_e32 v63, v2
	v_mov_b32_e32 v64, v2
	v_mov_b32_e32 v65, v2
	v_mov_b32_e32 v66, v2
	v_mov_b32_e32 v67, v2
	v_mov_b32_e32 v68, v2
	v_mov_b32_e32 v69, v2
	v_mov_b32_e32 v70, v2
	v_mov_b32_e32 v71, v2
	v_mov_b32_e32 v72, v2
	v_mov_b32_e32 v73, v2
	v_mov_b32_e32 v82, v2
	v_mov_b32_e32 v83, v2
	v_mov_b32_e32 v84, v2
	v_mov_b32_e32 v85, v2
	v_mov_b32_e32 v86, v2
	v_mov_b32_e32 v87, v2
	v_mov_b32_e32 v88, v2
	v_mov_b32_e32 v89, v2
	v_mov_b32_e32 v98, v2
	v_mov_b32_e32 v99, v2
	v_mov_b32_e32 v100, v2
	v_mov_b32_e32 v101, v2
	v_mov_b32_e32 v102, v2
	v_mov_b32_e32 v103, v2
	v_mov_b32_e32 v104, v2
	v_mov_b32_e32 v105, v2
	v_mov_b32_e32 v114, v2
	v_mov_b32_e32 v115, v2
	v_mov_b32_e32 v116, v2
	v_mov_b32_e32 v117, v2
	v_mov_b32_e32 v118, v2
	v_mov_b32_e32 v119, v2
	v_mov_b32_e32 v120, v2
	v_mov_b32_e32 v121, v2
	v_mov_b32_e32 v74, v2
	v_mov_b32_e32 v75, v2
	v_mov_b32_e32 v76, v2
	v_mov_b32_e32 v77, v2
	v_mov_b32_e32 v78, v2
	v_mov_b32_e32 v79, v2
	v_mov_b32_e32 v80, v2
	v_mov_b32_e32 v81, v2
	v_mov_b32_e32 v90, v2
	v_mov_b32_e32 v91, v2
	v_mov_b32_e32 v92, v2
	v_mov_b32_e32 v93, v2
	v_mov_b32_e32 v94, v2
	v_mov_b32_e32 v95, v2
	v_mov_b32_e32 v96, v2
	v_mov_b32_e32 v97, v2
	v_mov_b32_e32 v106, v2
	v_mov_b32_e32 v107, v2
	v_mov_b32_e32 v108, v2
	v_mov_b32_e32 v109, v2
	v_mov_b32_e32 v110, v2
	v_mov_b32_e32 v111, v2
	v_mov_b32_e32 v112, v2
	v_mov_b32_e32 v113, v2
	v_mov_b32_e32 v122, v2
	v_mov_b32_e32 v123, v2
	v_mov_b32_e32 v124, v2
	v_mov_b32_e32 v125, v2
	v_mov_b32_e32 v126, v2
	v_mov_b32_e32 v127, v2
	v_mov_b32_e32 v128, v2
	v_mov_b32_e32 v129, v2
	s_waitcnt lgkmcnt(0)
	s_add_i32 s94, 0, 0x10000
	v_add_u32_e32 v0, s94, v170
	ds_read_b128 v[130:133], v0
	ds_read_b128 v[134:137], v0 offset:1024
	ds_read_b128 v[138:141], v0 offset:2048
	ds_read_b128 v[142:145], v0 offset:3072
	s_add_u32 s87, s88, 0xfffc0080
	s_addc_u32 s90, s89, -1
	s_cmp_eq_u32 s85, 12
	s_cselect_b32 s93, s13, s90
	s_cselect_b32 s92, s22, s87
	s_cselect_b32 s91, s7, s79
	s_cselect_b32 s90, s23, s34
.LBB0_1209:
	s_waitcnt lgkmcnt(0)
	v_lshl_add_u64 v[194:195], s[88:89], 0, v[154:155]
	s_add_i32 m0, s39, 0xc000
	ds_read_b128 v[158:161], v171
	ds_read_b128 v[162:165], v171 offset:1024
	ds_read_b128 v[166:169], v171 offset:2048
	ds_read_b128 v[172:175], v171 offset:3072
	ds_read_b128 v[176:179], v171 offset:4096
	ds_read_b128 v[180:183], v171 offset:5120
	ds_read_b128 v[184:187], v171 offset:6144
	ds_read_b128 v[190:193], v171 offset:7168
	global_load_lds_dwordx4 v[194:195], off
	s_add_i32 m0, s39, 0xe000
	v_lshl_add_u64 v[194:195], s[88:89], 0, v[156:157]
	global_load_lds_dwordx4 v[194:195], off
	s_waitcnt lgkmcnt(8)
	s_barrier
	s_waitcnt lgkmcnt(0)
	v_mfma_f32_16x16x32_bf16 v[126:129], v[130:133], v[158:161], v[126:129]
	v_mfma_f32_16x16x32_bf16 v[122:125], v[138:141], v[158:161], v[122:125]
	v_mfma_f32_16x16x32_bf16 v[110:113], v[130:133], v[166:169], v[110:113]
	v_mfma_f32_16x16x32_bf16 v[106:109], v[138:141], v[166:169], v[106:109]
	v_mfma_f32_16x16x32_bf16 v[94:97], v[130:133], v[176:179], v[94:97]
	v_mfma_f32_16x16x32_bf16 v[90:93], v[138:141], v[176:179], v[90:93]
	v_mfma_f32_16x16x32_bf16 v[78:81], v[130:133], v[184:187], v[78:81]
	v_mfma_f32_16x16x32_bf16 v[74:77], v[138:141], v[184:187], v[74:77]
	v_mfma_f32_16x16x32_bf16 v[126:129], v[134:137], v[162:165], v[126:129]
	v_mfma_f32_16x16x32_bf16 v[122:125], v[142:145], v[162:165], v[122:125]
	v_mfma_f32_16x16x32_bf16 v[110:113], v[134:137], v[172:175], v[110:113]
	v_mfma_f32_16x16x32_bf16 v[106:109], v[142:145], v[172:175], v[106:109]
	v_mfma_f32_16x16x32_bf16 v[94:97], v[134:137], v[180:183], v[94:97]
	v_mfma_f32_16x16x32_bf16 v[90:93], v[142:145], v[180:183], v[90:93]
	v_mfma_f32_16x16x32_bf16 v[78:81], v[134:137], v[190:193], v[78:81]
	v_mfma_f32_16x16x32_bf16 v[74:77], v[142:145], v[190:193], v[74:77]
	s_barrier
	s_add_i32 s87, 0, 0x14000
	s_add_i32 s94, s94, s38
	v_add_u32_e32 v0, s87, v170
	v_lshl_add_u64 v[210:211], s[90:91], 0, v[148:149]
	s_mov_b32 m0, s94
	ds_read_b128 v[194:197], v0
	ds_read_b128 v[198:201], v0 offset:1024
	ds_read_b128 v[202:205], v0 offset:2048
	ds_read_b128 v[206:209], v0 offset:3072
	global_load_lds_dwordx4 v[210:211], off
	s_add_i32 m0, s94, 0x2000
	v_lshl_add_u64 v[212:213], s[90:91], 0, v[152:153]
	global_load_lds_dwordx4 v[212:213], off
	s_barrier
	s_waitcnt lgkmcnt(0)
	v_mfma_f32_16x16x32_bf16 v[118:121], v[194:197], v[158:161], v[118:121]
	v_mfma_f32_16x16x32_bf16 v[114:117], v[202:205], v[158:161], v[114:117]
	v_mfma_f32_16x16x32_bf16 v[102:105], v[194:197], v[166:169], v[102:105]
	v_mfma_f32_16x16x32_bf16 v[98:101], v[202:205], v[166:169], v[98:101]
	v_mfma_f32_16x16x32_bf16 v[86:89], v[194:197], v[176:179], v[86:89]
	v_mfma_f32_16x16x32_bf16 v[82:85], v[202:205], v[176:179], v[82:85]
	v_mfma_f32_16x16x32_bf16 v[70:73], v[194:197], v[184:187], v[70:73]
	v_mfma_f32_16x16x32_bf16 v[66:69], v[202:205], v[184:187], v[66:69]
	v_mfma_f32_16x16x32_bf16 v[118:121], v[198:201], v[162:165], v[118:121]
	v_mfma_f32_16x16x32_bf16 v[114:117], v[206:209], v[162:165], v[114:117]
	v_mfma_f32_16x16x32_bf16 v[102:105], v[198:201], v[172:175], v[102:105]
	v_mfma_f32_16x16x32_bf16 v[98:101], v[206:209], v[172:175], v[98:101]
	v_mfma_f32_16x16x32_bf16 v[86:89], v[198:201], v[180:183], v[86:89]
	v_mfma_f32_16x16x32_bf16 v[82:85], v[206:209], v[180:183], v[82:85]
	v_mfma_f32_16x16x32_bf16 v[70:73], v[198:201], v[190:193], v[70:73]
	v_mfma_f32_16x16x32_bf16 v[66:69], v[206:209], v[190:193], v[66:69]
	s_mov_b32 m0, s39
	v_lshl_add_u64 v[214:215], s[92:93], 0, v[146:147]
	s_barrier
	ds_read_b128 v[158:161], v171 offset:16384
	ds_read_b128 v[162:165], v171 offset:17408
	ds_read_b128 v[166:169], v171 offset:18432
	ds_read_b128 v[172:175], v171 offset:19456
	ds_read_b128 v[176:179], v171 offset:20480
	ds_read_b128 v[180:183], v171 offset:21504
	ds_read_b128 v[184:187], v171 offset:22528
	ds_read_b128 v[190:193], v171 offset:23552
	global_load_lds_dwordx4 v[214:215], off
	s_mov_b32 m0, s42
	v_lshl_add_u64 v[216:217], s[92:93], 0, v[150:151]
	global_load_lds_dwordx4 v[216:217], off
	s_waitcnt vmcnt(10)
	s_barrier
	s_waitcnt lgkmcnt(0)
	v_mfma_f32_16x16x32_bf16 v[62:65], v[130:133], v[158:161], v[62:65]
	v_mfma_f32_16x16x32_bf16 v[58:61], v[138:141], v[158:161], v[58:61]
	v_mfma_f32_16x16x32_bf16 v[46:49], v[130:133], v[166:169], v[46:49]
	v_mfma_f32_16x16x32_bf16 v[42:45], v[138:141], v[166:169], v[42:45]
	v_mfma_f32_16x16x32_bf16 v[30:33], v[130:133], v[176:179], v[30:33]
	v_mfma_f32_16x16x32_bf16 v[26:29], v[138:141], v[176:179], v[26:29]
	v_mfma_f32_16x16x32_bf16 v[14:17], v[130:133], v[184:187], v[14:17]
	v_mfma_f32_16x16x32_bf16 v[10:13], v[138:141], v[184:187], v[10:13]
	v_mfma_f32_16x16x32_bf16 v[62:65], v[134:137], v[162:165], v[62:65]
	v_mfma_f32_16x16x32_bf16 v[58:61], v[142:145], v[162:165], v[58:61]
	v_mfma_f32_16x16x32_bf16 v[46:49], v[134:137], v[172:175], v[46:49]
	v_mfma_f32_16x16x32_bf16 v[42:45], v[142:145], v[172:175], v[42:45]
	v_mfma_f32_16x16x32_bf16 v[30:33], v[134:137], v[180:183], v[30:33]
	v_mfma_f32_16x16x32_bf16 v[26:29], v[142:145], v[180:183], v[26:29]
	v_mfma_f32_16x16x32_bf16 v[14:17], v[134:137], v[190:193], v[14:17]
	v_mfma_f32_16x16x32_bf16 v[10:13], v[142:145], v[190:193], v[10:13]
	s_barrier
	s_add_u32 s94, s90, 0x40000
	s_addc_u32 s95, s91, 0
	s_add_i32 s87, s87, s38
	s_mov_b32 m0, s87
	v_lshl_add_u64 v[130:131], s[94:95], 0, v[148:149]
	global_load_lds_dwordx4 v[130:131], off
	s_add_i32 m0, s87, 0x2000
	v_lshl_add_u64 v[130:131], s[94:95], 0, v[152:153]
	global_load_lds_dwordx4 v[130:131], off
	s_add_i32 s87, 0, 0x18000
	v_add_u32_e32 v0, s87, v170
	ds_read_b128 v[130:133], v0
	ds_read_b128 v[134:137], v0 offset:1024
	ds_read_b128 v[138:141], v0 offset:2048
	ds_read_b128 v[142:145], v0 offset:3072
	s_waitcnt vmcnt(6)
	s_barrier
	v_mfma_f32_16x16x32_bf16 v[54:57], v[194:197], v[158:161], v[54:57]
	v_mfma_f32_16x16x32_bf16 v[50:53], v[202:205], v[158:161], v[50:53]
	v_mfma_f32_16x16x32_bf16 v[38:41], v[194:197], v[166:169], v[38:41]
	v_mfma_f32_16x16x32_bf16 v[34:37], v[202:205], v[166:169], v[34:37]
	v_mfma_f32_16x16x32_bf16 v[22:25], v[194:197], v[176:179], v[22:25]
	v_mfma_f32_16x16x32_bf16 v[18:21], v[202:205], v[176:179], v[18:21]
	v_mfma_f32_16x16x32_bf16 v[6:9], v[194:197], v[184:187], v[6:9]
	v_mfma_f32_16x16x32_bf16 v[2:5], v[202:205], v[184:187], v[2:5]
	v_mfma_f32_16x16x32_bf16 v[54:57], v[198:201], v[162:165], v[54:57]
	v_mfma_f32_16x16x32_bf16 v[50:53], v[206:209], v[162:165], v[50:53]
	v_mfma_f32_16x16x32_bf16 v[38:41], v[198:201], v[172:175], v[38:41]
	v_mfma_f32_16x16x32_bf16 v[34:37], v[206:209], v[172:175], v[34:37]
	v_mfma_f32_16x16x32_bf16 v[22:25], v[198:201], v[180:183], v[22:25]
	v_mfma_f32_16x16x32_bf16 v[18:21], v[206:209], v[180:183], v[18:21]
	v_mfma_f32_16x16x32_bf16 v[6:9], v[198:201], v[190:193], v[6:9]
	v_mfma_f32_16x16x32_bf16 v[2:5], v[206:209], v[190:193], v[2:5]
	s_barrier
	s_add_u32 s92, s92, 0x40000
	s_addc_u32 s93, s93, 0
	s_mov_b32 m0, s43
	v_lshl_add_u64 v[194:195], s[92:93], 0, v[146:147]
	ds_read_b128 v[158:161], v171 offset:32768
	ds_read_b128 v[162:165], v171 offset:33792
	ds_read_b128 v[166:169], v171 offset:34816
	ds_read_b128 v[172:175], v171 offset:35840
	ds_read_b128 v[176:179], v171 offset:36864
	ds_read_b128 v[180:183], v171 offset:37888
	ds_read_b128 v[184:187], v171 offset:38912
	ds_read_b128 v[190:193], v171 offset:39936
	global_load_lds_dwordx4 v[194:195], off
	s_mov_b32 m0, s44
	v_lshl_add_u64 v[194:195], s[92:93], 0, v[150:151]
	global_load_lds_dwordx4 v[194:195], off
	s_waitcnt lgkmcnt(8)
	s_barrier
	s_waitcnt lgkmcnt(0)
	v_mfma_f32_16x16x32_bf16 v[126:129], v[130:133], v[158:161], v[126:129]
	v_mfma_f32_16x16x32_bf16 v[122:125], v[138:141], v[158:161], v[122:125]
	v_mfma_f32_16x16x32_bf16 v[110:113], v[130:133], v[166:169], v[110:113]
	v_mfma_f32_16x16x32_bf16 v[106:109], v[138:141], v[166:169], v[106:109]
	v_mfma_f32_16x16x32_bf16 v[94:97], v[130:133], v[176:179], v[94:97]
	v_mfma_f32_16x16x32_bf16 v[90:93], v[138:141], v[176:179], v[90:93]
	v_mfma_f32_16x16x32_bf16 v[78:81], v[130:133], v[184:187], v[78:81]
	v_mfma_f32_16x16x32_bf16 v[74:77], v[138:141], v[184:187], v[74:77]
	v_mfma_f32_16x16x32_bf16 v[126:129], v[134:137], v[162:165], v[126:129]
	v_mfma_f32_16x16x32_bf16 v[122:125], v[142:145], v[162:165], v[122:125]
	v_mfma_f32_16x16x32_bf16 v[110:113], v[134:137], v[172:175], v[110:113]
	v_mfma_f32_16x16x32_bf16 v[106:109], v[142:145], v[172:175], v[106:109]
	v_mfma_f32_16x16x32_bf16 v[94:97], v[134:137], v[180:183], v[94:97]
	v_mfma_f32_16x16x32_bf16 v[90:93], v[142:145], v[180:183], v[90:93]
	v_mfma_f32_16x16x32_bf16 v[78:81], v[134:137], v[190:193], v[78:81]
	v_mfma_f32_16x16x32_bf16 v[74:77], v[142:145], v[190:193], v[74:77]
	s_barrier
	s_add_i32 s92, 0, 0x1c000
	s_add_i32 s87, s87, s38
	v_add_u32_e32 v0, s92, v170
	v_lshl_add_u64 v[210:211], v[210:211], 0, s[40:41]
	s_mov_b32 m0, s87
	ds_read_b128 v[194:197], v0
	ds_read_b128 v[198:201], v0 offset:1024
	ds_read_b128 v[202:205], v0 offset:2048
	ds_read_b128 v[206:209], v0 offset:3072
	global_load_lds_dwordx4 v[210:211], off
	s_add_i32 m0, s87, 0x2000
	v_lshl_add_u64 v[210:211], v[212:213], 0, s[40:41]
	global_load_lds_dwordx4 v[210:211], off
	s_barrier
	s_waitcnt lgkmcnt(0)
	v_mfma_f32_16x16x32_bf16 v[118:121], v[194:197], v[158:161], v[118:121]
	v_mfma_f32_16x16x32_bf16 v[114:117], v[202:205], v[158:161], v[114:117]
	v_mfma_f32_16x16x32_bf16 v[102:105], v[194:197], v[166:169], v[102:105]
	v_mfma_f32_16x16x32_bf16 v[98:101], v[202:205], v[166:169], v[98:101]
	v_mfma_f32_16x16x32_bf16 v[86:89], v[194:197], v[176:179], v[86:89]
	v_mfma_f32_16x16x32_bf16 v[82:85], v[202:205], v[176:179], v[82:85]
	v_mfma_f32_16x16x32_bf16 v[70:73], v[194:197], v[184:187], v[70:73]
	v_mfma_f32_16x16x32_bf16 v[66:69], v[202:205], v[184:187], v[66:69]
	v_mfma_f32_16x16x32_bf16 v[118:121], v[198:201], v[162:165], v[118:121]
	v_mfma_f32_16x16x32_bf16 v[114:117], v[206:209], v[162:165], v[114:117]
	v_mfma_f32_16x16x32_bf16 v[102:105], v[198:201], v[172:175], v[102:105]
	v_mfma_f32_16x16x32_bf16 v[98:101], v[206:209], v[172:175], v[98:101]
	v_mfma_f32_16x16x32_bf16 v[86:89], v[198:201], v[180:183], v[86:89]
	v_mfma_f32_16x16x32_bf16 v[82:85], v[206:209], v[180:183], v[82:85]
	v_mfma_f32_16x16x32_bf16 v[70:73], v[198:201], v[190:193], v[70:73]
	v_mfma_f32_16x16x32_bf16 v[66:69], v[206:209], v[190:193], v[66:69]
	s_mov_b32 m0, s60
	v_lshl_add_u64 v[210:211], v[214:215], 0, s[40:41]
	s_barrier
	ds_read_b128 v[158:161], v171 offset:49152
	ds_read_b128 v[162:165], v171 offset:50176
	ds_read_b128 v[166:169], v171 offset:51200
	ds_read_b128 v[172:175], v171 offset:52224
	ds_read_b128 v[176:179], v171 offset:53248
	ds_read_b128 v[180:183], v171 offset:54272
	ds_read_b128 v[184:187], v171 offset:55296
	ds_read_b128 v[190:193], v171 offset:56320
	global_load_lds_dwordx4 v[210:211], off
	s_mov_b32 m0, s61
	v_lshl_add_u64 v[210:211], v[216:217], 0, s[40:41]
	global_load_lds_dwordx4 v[210:211], off
	s_waitcnt vmcnt(10)
	s_barrier
	s_waitcnt lgkmcnt(0)
	v_mfma_f32_16x16x32_bf16 v[62:65], v[130:133], v[158:161], v[62:65]
	v_mfma_f32_16x16x32_bf16 v[58:61], v[138:141], v[158:161], v[58:61]
	v_mfma_f32_16x16x32_bf16 v[46:49], v[130:133], v[166:169], v[46:49]
	v_mfma_f32_16x16x32_bf16 v[42:45], v[138:141], v[166:169], v[42:45]
	v_mfma_f32_16x16x32_bf16 v[30:33], v[130:133], v[176:179], v[30:33]
	v_mfma_f32_16x16x32_bf16 v[26:29], v[138:141], v[176:179], v[26:29]
	v_mfma_f32_16x16x32_bf16 v[14:17], v[130:133], v[184:187], v[14:17]
	v_mfma_f32_16x16x32_bf16 v[10:13], v[138:141], v[184:187], v[10:13]
	v_mfma_f32_16x16x32_bf16 v[62:65], v[134:137], v[162:165], v[62:65]
	v_mfma_f32_16x16x32_bf16 v[58:61], v[142:145], v[162:165], v[58:61]
	v_mfma_f32_16x16x32_bf16 v[46:49], v[134:137], v[172:175], v[46:49]
	v_mfma_f32_16x16x32_bf16 v[42:45], v[142:145], v[172:175], v[42:45]
	v_mfma_f32_16x16x32_bf16 v[30:33], v[134:137], v[180:183], v[30:33]
	v_mfma_f32_16x16x32_bf16 v[26:29], v[142:145], v[180:183], v[26:29]
	v_mfma_f32_16x16x32_bf16 v[14:17], v[134:137], v[190:193], v[14:17]
	v_mfma_f32_16x16x32_bf16 v[10:13], v[142:145], v[190:193], v[10:13]
	s_barrier
	s_add_u32 s90, s90, 0x40080
	s_addc_u32 s91, s91, 0
	s_add_i32 s87, s92, s38
	s_mov_b32 m0, s87
	v_lshl_add_u64 v[130:131], s[90:91], 0, v[148:149]
	global_load_lds_dwordx4 v[130:131], off
	s_add_i32 m0, s87, 0x2000
	v_lshl_add_u64 v[130:131], s[90:91], 0, v[152:153]
	global_load_lds_dwordx4 v[130:131], off
	s_add_i32 s94, 0, 0x10000
	v_add_u32_e32 v0, s94, v170
	ds_read_b128 v[130:133], v0
	ds_read_b128 v[134:137], v0 offset:1024
	ds_read_b128 v[138:141], v0 offset:2048
	ds_read_b128 v[142:145], v0 offset:3072
	s_waitcnt vmcnt(6)
	s_barrier
	v_mfma_f32_16x16x32_bf16 v[54:57], v[194:197], v[158:161], v[54:57]
	v_mfma_f32_16x16x32_bf16 v[50:53], v[202:205], v[158:161], v[50:53]
	v_mfma_f32_16x16x32_bf16 v[38:41], v[194:197], v[166:169], v[38:41]
	v_mfma_f32_16x16x32_bf16 v[34:37], v[202:205], v[166:169], v[34:37]
	v_mfma_f32_16x16x32_bf16 v[22:25], v[194:197], v[176:179], v[22:25]
	v_mfma_f32_16x16x32_bf16 v[18:21], v[202:205], v[176:179], v[18:21]
	v_mfma_f32_16x16x32_bf16 v[6:9], v[194:197], v[184:187], v[6:9]
	v_mfma_f32_16x16x32_bf16 v[2:5], v[202:205], v[184:187], v[2:5]
	v_mfma_f32_16x16x32_bf16 v[54:57], v[198:201], v[162:165], v[54:57]
	v_mfma_f32_16x16x32_bf16 v[50:53], v[206:209], v[162:165], v[50:53]
	v_mfma_f32_16x16x32_bf16 v[38:41], v[198:201], v[172:175], v[38:41]
	v_mfma_f32_16x16x32_bf16 v[34:37], v[206:209], v[172:175], v[34:37]
	v_mfma_f32_16x16x32_bf16 v[22:25], v[198:201], v[180:183], v[22:25]
	v_mfma_f32_16x16x32_bf16 v[18:21], v[206:209], v[180:183], v[18:21]
	v_mfma_f32_16x16x32_bf16 v[6:9], v[198:201], v[190:193], v[6:9]
	v_mfma_f32_16x16x32_bf16 v[2:5], v[206:209], v[190:193], v[2:5]
	s_add_i32 s85, s85, 2
	s_add_u32 s88, s88, 0x100
	s_addc_u32 s89, s89, 0
	s_add_u32 s34, s34, 0x100
	s_addc_u32 s79, s79, 0
	s_add_u32 s87, s88, 0xfffc0080
	s_addc_u32 s90, s89, -1
	s_cmp_eq_u32 s85, 12
	s_cselect_b32 s93, s13, s90
	s_cselect_b32 s92, s22, s87
	s_cselect_b32 s91, s7, s79
	s_cselect_b32 s90, s23, s34
	s_cmp_gt_u32 s85, 13
	s_barrier
	s_cbranch_scc0 .LBB0_1209
	s_waitcnt lgkmcnt(0)
	v_mov_b32_e32 v131, v252
	s_lshl_b32 s7, s86, 8
	v_and_b32_e32 v130, 63, v131
	v_or_b32_e32 v0, s72, v130
	v_lshrrev_b32_e32 v0, 1, v0
	v_and_or_b32 v132, v0, 63, s73
	v_add_u32_e32 v134, s7, v132
	v_ashrrev_i32_e32 v135, 31, v134
	v_and_b32_e32 v142, 1, v131
	v_lshlrev_b64 v[134:135], 6, v[134:135]
	v_lshl_add_u64 v[134:135], s[82:83], 0, v[134:135]
	v_lshlrev_b32_e32 v0, 5, v142
	v_lshl_add_u64 v[138:139], v[134:135], 0, v[0:1]
	global_load_dwordx4 v[134:137], v[138:139], off
	s_nop 0
	global_load_dwordx4 v[138:141], v[138:139], off offset:16
	v_lshlrev_b32_e32 v0, 2, v130
	v_cmp_eq_u32_e32 vcc, 0, v142
	s_waitcnt vmcnt(0)
	v_add_f32_e32 v133, v134, v135
	v_add_f32_e32 v134, v136, v137
	v_add_f32_e32 v135, v138, v139
	v_add_f32_e32 v136, v140, v141
	v_add_f32_e32 v133, v133, v134
	v_add_f32_e32 v134, v135, v136
	v_add_f32_e32 v133, v133, v134
	v_xor_b32_e32 v134, 4, v0
	ds_bpermute_b32 v134, v134, v133
	s_and_saveexec_b64 s[22:23], vcc
	s_cbranch_execz .LBB0_1212
	s_waitcnt lgkmcnt(0)
	v_add_f32_e32 v133, v133, v134
	v_fmamk_f32 v133, v133, 0x3a800000, v224
	s_mov_b32 s13, 0x800000
	v_mul_f32_e32 v134, 0x4b800000, v133
	v_cmp_gt_f32_e32 vcc, s13, v133
	v_lshl_add_u32 v132, v132, 2, 0
	v_add_u32_e32 v132, 0x20000, v132
	v_cndmask_b32_e32 v133, v133, v134, vcc
	v_rsq_f32_e32 v133, v133
	s_nop 0
	v_mul_f32_e32 v134, 0x45800000, v133
	v_cndmask_b32_e32 v133, v133, v134, vcc
	ds_write_b32 v132, v133
